# v71 + 64-byte alignment of the non-GEMM hot loop heads (attention unit/tile loops, pooling loops, final-norm loop, prep loops); placement only
# baseline (speedup 1.0000x reference)
.LBB0_22:
	s_add_i32 s43, s43, s72
	s_add_i32 s35, s35, s36
	s_add_i32 s37, s37, s38
	s_cmpk_gt_i32 s43, 0x54ff
	s_cbranch_scc1 .LBB0_64
	.p2align	6

.LBB0_64:
	v_writelane_b32 v251, s96, 51
	s_lshl_b32 s55, s2, 9
	s_lshl_b32 s3, s94, 9
	v_writelane_b32 v251, s97, 52
	v_writelane_b32 v251, s92, 53
	s_nop 1
	v_writelane_b32 v251, s93, 54
	v_writelane_b32 v251, s90, 55
	s_nop 1
	v_writelane_b32 v251, s91, 56
	s_nop 0
	v_readlane_b32 s0, v251, 25
	s_cmpk_gt_i32 s0, 0x7ff
	v_readlane_b32 s4, v251, 35
	v_readlane_b32 s1, v251, 26
	v_readlane_b32 s5, v251, 36
	v_readlane_b32 s6, v251, 37
	v_readlane_b32 s7, v251, 38
	v_readlane_b32 s8, v251, 39
	v_readlane_b32 s9, v251, 40
	v_readlane_b32 s10, v251, 41
	v_readlane_b32 s11, v251, 42
	v_readlane_b32 s12, v251, 43
	v_readlane_b32 s13, v251, 44
	v_readlane_b32 s14, v251, 45
	v_readlane_b32 s15, v251, 46
	v_readlane_b32 s16, v251, 47
	v_readlane_b32 s17, v251, 48
	v_readlane_b32 s18, v251, 49
	v_readlane_b32 s19, v251, 50
	s_cbranch_scc1 .LBB0_67
	v_readlane_b32 s0, v251, 24
	s_lshl_b32 s0, s0, 6
	v_readlane_b32 s4, v251, 35
	s_add_i32 s80, s55, s0
	v_readlane_b32 s0, v251, 25
	v_lshlrev_b32_e32 v0, 1, v223
	v_mov_b32_e32 v5, 0
	v_lshlrev_b32_e32 v4, 3, v223
	v_readlane_b32 s6, v251, 37
	v_readlane_b32 s7, v251, 38
	v_readlane_b32 s1, v251, 26
	v_lshlrev_b32_e32 v18, 2, v0
	v_lshl_add_u64 v[6:7], s[6:7], 0, v[4:5]
	s_movk_i32 s81, 0x7fff
	s_mov_b32 s82, 0xffff0000
	s_mov_b32 s83, s0
	s_mov_b32 s1, 0
	v_readlane_b32 s5, v251, 36
	v_readlane_b32 s8, v251, 39
	v_readlane_b32 s9, v251, 40
	v_readlane_b32 s10, v251, 41
	v_readlane_b32 s11, v251, 42
	v_readlane_b32 s12, v251, 43
	v_readlane_b32 s13, v251, 44
	v_readlane_b32 s14, v251, 45
	v_readlane_b32 s15, v251, 46
	v_readlane_b32 s16, v251, 47
	v_readlane_b32 s17, v251, 48
	v_readlane_b32 s18, v251, 49
	v_readlane_b32 s19, v251, 50
	.p2align	6

.LBB0_81:
	s_or_b64 exec, exec, s[24:25]
	s_add_i32 s27, s27, s0
	s_add_u32 s18, s18, s20
	s_addc_u32 s19, s19, s21
	s_add_u32 s22, s22, s20
	s_addc_u32 s23, s23, s21
	v_lshl_add_u64 v[16:17], v[16:17], 0, s[14:15]
	v_lshl_add_u64 v[18:19], v[18:19], 0, s[16:17]
	v_lshl_add_u64 v[22:23], v[22:23], 0, s[14:15]
	s_cmp_lt_i32 s27, 0x8000
	v_lshl_add_u64 v[24:25], v[24:25], 0, s[16:17]
	s_cbranch_scc0 .LBB0_86
	.p2align	6

.LBB0_564:
	v_readlane_b32 s0, v253, 45
	v_readlane_b32 s1, v253, 46
	s_add_i32 s45, s45, s73
	s_xor_b64 s[10:11], s[10:11], s[0:1]
	s_cmp_ge_i32 s45, s95
	s_cbranch_scc1 .LBB0_611
	.p2align	6
.LBB0_565:
	s_and_b32 s60, s45, 1
	s_bfe_u32 s59, s45, 0x60001
	s_ashr_i32 s0, s45, 7
	s_lshl_b32 s1, s60, 2
	s_lshl_b32 s50, s59, 7
	s_add_i32 s16, s1, s20
	s_ashr_i32 s1, s0, 31
	s_add_i32 s51, s50, 0xffffff80
	s_lshl_b64 s[18:19], s[0:1], 13
	v_or_b32_e32 v0, s50, v112
	v_add_u32_e32 v6, s51, v119
	v_or_b32_e32 v0, s18, v0
	v_mov_b64_e32 v[4:5], s[56:57]
	v_cmp_gt_u32_e32 vcc, s37, v6
	v_mad_u64_u32 v[0:1], s[66:67], v0, s53, v[4:5]
	s_lshl_b32 s18, s16, 6
	s_lshl_b32 s17, s0, 13
	v_cndmask_b32_e32 v28, 0, v6, vcc
	v_mad_i32_i24 v1, s19, v207, v1
	s_ashr_i32 s19, s18, 31
	v_add_u32_e32 v6, s17, v28
	v_lshl_add_u64 v[0:1], s[18:19], 1, v[0:1]
	v_lshlrev_b32_e32 v152, 1, v84
	v_mad_i64_i32 v[4:5], s[18:19], v6, s53, v[4:5]
	s_lshl_b32 s8, s60, 7
	v_lshl_add_u64 v[106:107], v[0:1], 0, v[152:153]
	v_lshl_add_u64 v[4:5], v[4:5], 0, s[8:9]
	v_lshlrev_b32_e32 v152, 1, v86
	v_lshl_add_u64 v[4:5], v[4:5], 0, v[152:153]
	global_load_dwordx4 v[0:3], v[106:107], off
	global_load_dwordx4 v[8:11], v[106:107], off offset:64
	v_add_u32_e32 v12, s51, v119
	v_cmp_gt_u32_e32 vcc, s37, v12
	s_nop 1
	v_cndmask_b32_e32 v29, 0, v12, vcc
	v_add_u32_e32 v12, s17, v29
	v_mov_b64_e32 v[14:15], s[56:57]
	v_mad_i64_i32 v[14:15], s[18:19], v12, s53, v[14:15]
	v_lshl_add_u64 v[14:15], v[14:15], 0, s[8:9]
	v_lshl_add_u64 v[14:15], v[14:15], 0, v[152:153]
	global_load_dwordx4 v[44:47], v[14:15], off offset:1024
	v_add_u32_e32 v12, s51, v120
	v_cmp_gt_u32_e32 vcc, s37, v12
	s_nop 1
	v_cndmask_b32_e32 v29, 0, v12, vcc
	v_add_u32_e32 v12, s17, v29
	v_mov_b64_e32 v[14:15], s[56:57]
	v_mad_i64_i32 v[14:15], s[18:19], v12, s53, v[14:15]
	v_lshl_add_u64 v[14:15], v[14:15], 0, s[8:9]
	v_lshl_add_u64 v[14:15], v[14:15], 0, v[152:153]
	global_load_dwordx4 v[48:51], v[14:15], off offset:1024
	v_add_u32_e32 v12, s51, v121
	v_cmp_gt_u32_e32 vcc, s37, v12
	s_nop 1
	v_cndmask_b32_e32 v29, 0, v12, vcc
	v_add_u32_e32 v12, s17, v29
	v_mov_b64_e32 v[14:15], s[56:57]
	v_mad_i64_i32 v[14:15], s[18:19], v12, s53, v[14:15]
	v_lshl_add_u64 v[14:15], v[14:15], 0, s[8:9]
	v_lshl_add_u64 v[14:15], v[14:15], 0, v[152:153]
	global_load_dwordx4 v[52:55], v[14:15], off offset:1024
	v_add_u32_e32 v12, s51, v122
	v_cmp_gt_u32_e32 vcc, s37, v12
	s_nop 1
	v_cndmask_b32_e32 v29, 0, v12, vcc
	v_add_u32_e32 v12, s17, v29
	v_mov_b64_e32 v[14:15], s[56:57]
	v_mad_i64_i32 v[14:15], s[18:19], v12, s53, v[14:15]
	v_lshl_add_u64 v[14:15], v[14:15], 0, s[8:9]
	v_lshl_add_u64 v[14:15], v[14:15], 0, v[152:153]
	global_load_dwordx4 v[56:59], v[14:15], off offset:1024
	v_add_u32_e32 v12, s51, v123
	v_cmp_gt_u32_e32 vcc, s37, v12
	s_nop 1
	v_cndmask_b32_e32 v29, 0, v12, vcc
	v_add_u32_e32 v12, s17, v29
	v_mov_b64_e32 v[14:15], s[56:57]
	v_mad_i64_i32 v[14:15], s[18:19], v12, s53, v[14:15]
	v_lshl_add_u64 v[14:15], v[14:15], 0, s[8:9]
	v_lshl_add_u64 v[14:15], v[14:15], 0, v[152:153]
	global_load_dwordx4 v[60:63], v[14:15], off offset:1024
	v_add_u32_e32 v12, s51, v124
	v_cmp_gt_u32_e32 vcc, s37, v12
	s_nop 1
	v_cndmask_b32_e32 v29, 0, v12, vcc
	v_add_u32_e32 v12, s17, v29
	v_mov_b64_e32 v[14:15], s[56:57]
	v_mad_i64_i32 v[14:15], s[18:19], v12, s53, v[14:15]
	v_lshl_add_u64 v[14:15], v[14:15], 0, s[8:9]
	v_lshl_add_u64 v[14:15], v[14:15], 0, v[152:153]
	global_load_dwordx4 v[64:67], v[14:15], off offset:1024
	s_and_saveexec_b64 s[18:19], s[46:47]
	v_add_u32_e32 v12, s51, v119
	v_cmp_gt_u32_e32 vcc, s37, v12
	s_nop 1
	v_cndmask_b32_e32 v29, 0, v12, vcc
	v_lshlrev_b32_e32 v12, 4, v29
	v_ashrrev_i32_e32 v13, 31, v12
	v_lshl_add_u64 v[16:17], v[12:13], 2, s[12:13]
	global_load_dwordx4 v[68:71], v[16:17], off
	global_load_dwordx4 v[72:75], v[16:17], off offset:16
	global_load_dwordx4 v[76:79], v[16:17], off offset:32
	global_load_dwordx4 v[80:83], v[16:17], off offset:48
	v_add_u32_e32 v12, s51, v120
	v_cmp_gt_u32_e32 vcc, s37, v12
	s_nop 1
	v_cndmask_b32_e32 v29, 0, v12, vcc
	v_lshlrev_b32_e32 v12, 4, v29
	v_ashrrev_i32_e32 v13, 31, v12
	v_lshl_add_u64 v[16:17], v[12:13], 2, s[12:13]
	global_load_dwordx4 v[176:179], v[16:17], off
	global_load_dwordx4 v[180:183], v[16:17], off offset:16
	global_load_dwordx4 v[184:187], v[16:17], off offset:32
	global_load_dwordx4 v[188:191], v[16:17], off offset:48
	v_add_u32_e32 v12, s51, v121
	v_cmp_gt_u32_e32 vcc, s37, v12
	s_nop 1
	v_cndmask_b32_e32 v29, 0, v12, vcc
	v_lshlrev_b32_e32 v12, 4, v29
	v_ashrrev_i32_e32 v13, 31, v12
	v_lshl_add_u64 v[16:17], v[12:13], 2, s[12:13]
	global_load_dwordx4 v[192:195], v[16:17], off
	global_load_dwordx4 v[196:199], v[16:17], off offset:16
	global_load_dwordx4 v[144:147], v[16:17], off offset:32
	global_load_dwordx4 v[148:151], v[16:17], off offset:48
	v_add_u32_e32 v12, s51, v122
	v_cmp_gt_u32_e32 vcc, s37, v12
	s_nop 1
	v_cndmask_b32_e32 v29, 0, v12, vcc
	v_lshlrev_b32_e32 v12, 4, v29
	v_ashrrev_i32_e32 v13, 31, v12
	v_lshl_add_u64 v[16:17], v[12:13], 2, s[12:13]
	global_load_dwordx4 v[210:213], v[16:17], off
	global_load_dwordx4 v[214:217], v[16:17], off offset:16
	global_load_dwordx4 v[218:221], v[16:17], off offset:32
	global_load_dwordx4 v[224:227], v[16:17], off offset:48
	v_add_u32_e32 v12, s51, v123
	v_cmp_gt_u32_e32 vcc, s37, v12
	s_nop 1
	v_cndmask_b32_e32 v29, 0, v12, vcc
	v_lshlrev_b32_e32 v12, 4, v29
	v_ashrrev_i32_e32 v13, 31, v12
	v_lshl_add_u64 v[16:17], v[12:13], 2, s[12:13]
	global_load_dwordx4 v[228:231], v[16:17], off
	global_load_dwordx4 v[232:235], v[16:17], off offset:16
	global_load_dwordx4 v[236:239], v[16:17], off offset:32
	global_load_dwordx4 v[172:175], v[16:17], off offset:48
	s_or_b64 exec, exec, s[18:19]
	s_barrier
	s_waitcnt vmcnt(16)
	v_add_u32_e32 v12, s51, v119
	v_cmp_gt_u32_e32 vcc, s37, v12
	s_nop 1
	v_cndmask_b32_e32 v7, 0, v47, vcc
	v_cndmask_b32_e32 v6, 0, v46, vcc
	v_cndmask_b32_e32 v5, 0, v45, vcc
	v_cndmask_b32_e32 v4, 0, v44, vcc
	v_lshlrev_b32_e32 v13, 16, v5
	v_lshlrev_b32_e32 v12, 16, v4
	v_and_b32_e32 v15, 0xffff0000, v5
	v_and_b32_e32 v14, 0xffff0000, v4
	v_and_b32_e32 v17, 0xffff0000, v6
	v_lshlrev_b32_e32 v16, 16, v6
	v_and_b32_e32 v19, 0xffff0000, v7
	v_lshlrev_b32_e32 v18, 16, v7
	ds_bpermute_b32 v26, v113, v12
	ds_bpermute_b32 v24, v113, v14
	ds_bpermute_b32 v27, v113, v13
	ds_bpermute_b32 v25, v113, v15
	ds_bpermute_b32 v22, v113, v16
	ds_bpermute_b32 v23, v113, v17
	ds_bpermute_b32 v20, v113, v18
	ds_bpermute_b32 v21, v113, v19
	s_and_saveexec_b64 s[18:19], s[46:47]
	s_waitcnt lgkmcnt(4)
	v_pk_mul_f32 v[24:25], v[88:89], v[24:25]
	s_waitcnt lgkmcnt(2)
	v_pk_mul_f32 v[22:23], v[88:89], v[22:23]
	s_waitcnt lgkmcnt(0)
	v_pk_mul_f32 v[20:21], v[88:89], v[20:21]
	v_pk_mul_f32 v[26:27], v[88:89], v[26:27]
	v_mov_b32_e32 v40, v68
	v_mov_b32_e32 v41, v70
	v_mov_b32_e32 v42, v76
	v_mov_b32_e32 v43, v78
	v_mov_b32_e32 v30, v77
	v_mov_b32_e32 v31, v79
	v_mov_b32_e32 v6, v69
	v_mov_b32_e32 v7, v71
	v_pk_mul_f32 v[4:5], v[22:23], v[80:81]
	v_pk_mul_f32 v[20:21], v[20:21], v[82:83]
	v_pk_mul_f32 v[24:25], v[24:25], v[30:31]
	v_pk_mul_f32 v[22:23], v[26:27], v[42:43]
	v_pk_fma_f32 v[4:5], v[72:73], v[16:17], v[4:5]
	v_pk_fma_f32 v[16:17], v[74:75], v[18:19], v[20:21]
	v_pk_fma_f32 v[6:7], v[6:7], v[14:15], v[24:25]
	v_pk_fma_f32 v[12:13], v[40:41], v[12:13], v[22:23]
	v_cvt_pk_bf16_f32 v14, v4, v5
	v_cvt_pk_bf16_f32 v5, v13, v7
	v_cvt_pk_bf16_f32 v4, v12, v6
	v_cvt_pk_bf16_f32 v7, v16, v17
	v_mov_b32_e32 v6, v14
	s_or_b64 exec, exec, s[18:19]
	ds_write_b128 v85, v[4:7]
	s_and_saveexec_b64 s[18:19], s[46:47]
	v_add_u32_e32 v12, s51, v124
	v_cmp_gt_u32_e32 vcc, s37, v12
	s_nop 1
	v_cndmask_b32_e32 v29, 0, v12, vcc
	v_lshlrev_b32_e32 v12, 4, v29
	v_ashrrev_i32_e32 v13, 31, v12
	v_lshl_add_u64 v[16:17], v[12:13], 2, s[12:13]
	global_load_dwordx4 v[68:71], v[16:17], off
	global_load_dwordx4 v[72:75], v[16:17], off offset:16
	global_load_dwordx4 v[76:79], v[16:17], off offset:32
	global_load_dwordx4 v[80:83], v[16:17], off offset:48
	s_or_b64 exec, exec, s[18:19]
	s_waitcnt vmcnt(16)
	v_add_u32_e32 v12, s51, v120
	v_cmp_gt_u32_e32 vcc, s37, v12
	s_nop 1
	v_cndmask_b32_e32 v7, 0, v51, vcc
	v_cndmask_b32_e32 v6, 0, v50, vcc
	v_cndmask_b32_e32 v5, 0, v49, vcc
	v_cndmask_b32_e32 v4, 0, v48, vcc
	v_lshlrev_b32_e32 v13, 16, v5
	v_lshlrev_b32_e32 v12, 16, v4
	v_and_b32_e32 v15, 0xffff0000, v5
	v_and_b32_e32 v14, 0xffff0000, v4
	v_and_b32_e32 v17, 0xffff0000, v6
	v_lshlrev_b32_e32 v16, 16, v6
	v_and_b32_e32 v19, 0xffff0000, v7
	v_lshlrev_b32_e32 v18, 16, v7
	ds_bpermute_b32 v26, v113, v12
	ds_bpermute_b32 v24, v113, v14
	ds_bpermute_b32 v27, v113, v13
	ds_bpermute_b32 v25, v113, v15
	ds_bpermute_b32 v22, v113, v16
	ds_bpermute_b32 v23, v113, v17
	ds_bpermute_b32 v20, v113, v18
	ds_bpermute_b32 v21, v113, v19
	s_and_saveexec_b64 s[18:19], s[46:47]
	s_waitcnt lgkmcnt(4)
	v_pk_mul_f32 v[24:25], v[88:89], v[24:25]
	s_waitcnt lgkmcnt(2)
	v_pk_mul_f32 v[22:23], v[88:89], v[22:23]
	s_waitcnt lgkmcnt(0)
	v_pk_mul_f32 v[20:21], v[88:89], v[20:21]
	v_pk_mul_f32 v[26:27], v[88:89], v[26:27]
	v_mov_b32_e32 v40, v176
	v_mov_b32_e32 v41, v178
	v_mov_b32_e32 v42, v184
	v_mov_b32_e32 v43, v186
	v_mov_b32_e32 v30, v185
	v_mov_b32_e32 v31, v187
	v_mov_b32_e32 v6, v177
	v_mov_b32_e32 v7, v179
	v_pk_mul_f32 v[4:5], v[22:23], v[188:189]
	v_pk_mul_f32 v[20:21], v[20:21], v[190:191]
	v_pk_mul_f32 v[24:25], v[24:25], v[30:31]
	v_pk_mul_f32 v[22:23], v[26:27], v[42:43]
	v_pk_fma_f32 v[4:5], v[180:181], v[16:17], v[4:5]
	v_pk_fma_f32 v[16:17], v[182:183], v[18:19], v[20:21]
	v_pk_fma_f32 v[6:7], v[6:7], v[14:15], v[24:25]
	v_pk_fma_f32 v[12:13], v[40:41], v[12:13], v[22:23]
	v_cvt_pk_bf16_f32 v14, v4, v5
	v_cvt_pk_bf16_f32 v5, v13, v7
	v_cvt_pk_bf16_f32 v4, v12, v6
	v_cvt_pk_bf16_f32 v7, v16, v17
	v_mov_b32_e32 v6, v14
	s_or_b64 exec, exec, s[18:19]
	ds_write_b128 v138, v[4:7]
	v_add_u32_e32 v12, s51, v125
	v_cmp_gt_u32_e32 vcc, s37, v12
	s_nop 1
	v_cndmask_b32_e32 v29, 0, v12, vcc
	v_add_u32_e32 v12, s17, v29
	v_mov_b64_e32 v[14:15], s[56:57]
	v_mad_i64_i32 v[14:15], s[18:19], v12, s53, v[14:15]
	v_lshl_add_u64 v[14:15], v[14:15], 0, s[8:9]
	v_lshl_add_u64 v[14:15], v[92:93], 1, v[14:15]
	global_load_dwordx4 v[44:47], v[14:15], off offset:1280
	v_add_u32_e32 v12, s51, v127
	v_cmp_gt_u32_e32 vcc, s37, v12
	s_nop 1
	v_cndmask_b32_e32 v29, 0, v12, vcc
	v_add_u32_e32 v12, s17, v29
	v_mov_b64_e32 v[14:15], s[56:57]
	v_mad_i64_i32 v[14:15], s[18:19], v12, s53, v[14:15]
	v_lshl_add_u64 v[14:15], v[14:15], 0, s[8:9]
	v_lshl_add_u64 v[14:15], v[94:95], 1, v[14:15]
	global_load_dwordx4 v[48:51], v[14:15], off offset:1280
	v_add_u32_e32 v12, s51, v129
	v_cmp_gt_u32_e32 vcc, s37, v12
	s_nop 1
	v_cndmask_b32_e32 v29, 0, v12, vcc
	v_add_u32_e32 v12, s17, v29
	v_mov_b64_e32 v[14:15], s[56:57]
	v_mad_i64_i32 v[14:15], s[18:19], v12, s53, v[14:15]
	v_lshl_add_u64 v[14:15], v[14:15], 0, s[8:9]
	v_lshl_add_u64 v[14:15], v[96:97], 1, v[14:15]
	global_load_dwordx4 v[176:179], v[14:15], off offset:1280
	v_add_u32_e32 v12, s51, v131
	v_cmp_gt_u32_e32 vcc, s37, v12
	s_nop 1
	v_cndmask_b32_e32 v29, 0, v12, vcc
	v_add_u32_e32 v12, s17, v29
	v_mov_b64_e32 v[14:15], s[56:57]
	v_mad_i64_i32 v[14:15], s[18:19], v12, s53, v[14:15]
	v_lshl_add_u64 v[14:15], v[14:15], 0, s[8:9]
	v_lshl_add_u64 v[14:15], v[98:99], 1, v[14:15]
	global_load_dwordx4 v[180:183], v[14:15], off offset:1280
	v_add_u32_e32 v12, s51, v133
	v_cmp_gt_u32_e32 vcc, s37, v12
	s_nop 1
	v_cndmask_b32_e32 v29, 0, v12, vcc
	v_add_u32_e32 v12, s17, v29
	v_mov_b64_e32 v[14:15], s[56:57]
	v_mad_i64_i32 v[14:15], s[18:19], v12, s53, v[14:15]
	v_lshl_add_u64 v[14:15], v[14:15], 0, s[8:9]
	v_lshl_add_u64 v[14:15], v[100:101], 1, v[14:15]
	global_load_dwordx4 v[184:187], v[14:15], off offset:1280
	v_add_u32_e32 v12, s51, v135
	v_cmp_gt_u32_e32 vcc, s37, v12
	s_nop 1
	v_cndmask_b32_e32 v29, 0, v12, vcc
	v_add_u32_e32 v12, s17, v29
	v_mov_b64_e32 v[14:15], s[56:57]
	v_mad_i64_i32 v[14:15], s[18:19], v12, s53, v[14:15]
	v_lshl_add_u64 v[14:15], v[14:15], 0, s[8:9]
	v_lshl_add_u64 v[14:15], v[102:103], 1, v[14:15]
	global_load_dwordx4 v[188:191], v[14:15], off offset:1280
	s_waitcnt vmcnt(18)
	v_add_u32_e32 v12, s51, v121
	v_cmp_gt_u32_e32 vcc, s37, v12
	s_nop 1
	v_cndmask_b32_e32 v7, 0, v55, vcc
	v_cndmask_b32_e32 v6, 0, v54, vcc
	v_cndmask_b32_e32 v5, 0, v53, vcc
	v_cndmask_b32_e32 v4, 0, v52, vcc
	v_lshlrev_b32_e32 v13, 16, v5
	v_lshlrev_b32_e32 v12, 16, v4
	v_and_b32_e32 v15, 0xffff0000, v5
	v_and_b32_e32 v14, 0xffff0000, v4
	v_and_b32_e32 v17, 0xffff0000, v6
	v_lshlrev_b32_e32 v16, 16, v6
	v_and_b32_e32 v19, 0xffff0000, v7
	v_lshlrev_b32_e32 v18, 16, v7
	ds_bpermute_b32 v26, v113, v12
	ds_bpermute_b32 v24, v113, v14
	ds_bpermute_b32 v27, v113, v13
	ds_bpermute_b32 v25, v113, v15
	ds_bpermute_b32 v22, v113, v16
	ds_bpermute_b32 v23, v113, v17
	ds_bpermute_b32 v20, v113, v18
	ds_bpermute_b32 v21, v113, v19
	s_and_saveexec_b64 s[18:19], s[46:47]
	s_waitcnt lgkmcnt(4)
	v_pk_mul_f32 v[24:25], v[88:89], v[24:25]
	s_waitcnt lgkmcnt(2)
	v_pk_mul_f32 v[22:23], v[88:89], v[22:23]
	s_waitcnt lgkmcnt(0)
	v_pk_mul_f32 v[20:21], v[88:89], v[20:21]
	v_pk_mul_f32 v[26:27], v[88:89], v[26:27]
	v_mov_b32_e32 v40, v192
	v_mov_b32_e32 v41, v194
	v_mov_b32_e32 v42, v144
	v_mov_b32_e32 v43, v146
	v_mov_b32_e32 v30, v145
	v_mov_b32_e32 v31, v147
	v_mov_b32_e32 v6, v193
	v_mov_b32_e32 v7, v195
	v_pk_mul_f32 v[4:5], v[22:23], v[148:149]
	v_pk_mul_f32 v[20:21], v[20:21], v[150:151]
	v_pk_mul_f32 v[24:25], v[24:25], v[30:31]
	v_pk_mul_f32 v[22:23], v[26:27], v[42:43]
	v_pk_fma_f32 v[4:5], v[196:197], v[16:17], v[4:5]
	v_pk_fma_f32 v[16:17], v[198:199], v[18:19], v[20:21]
	v_pk_fma_f32 v[6:7], v[6:7], v[14:15], v[24:25]
	v_pk_fma_f32 v[12:13], v[40:41], v[12:13], v[22:23]
	v_cvt_pk_bf16_f32 v14, v4, v5
	v_cvt_pk_bf16_f32 v5, v13, v7
	v_cvt_pk_bf16_f32 v4, v12, v6
	v_cvt_pk_bf16_f32 v7, v16, v17
	v_mov_b32_e32 v6, v14
	s_or_b64 exec, exec, s[18:19]
	ds_write_b128 v139, v[4:7]
	s_waitcnt vmcnt(14)
	v_add_u32_e32 v12, s51, v122
	v_cmp_gt_u32_e32 vcc, s37, v12
	s_nop 1
	v_cndmask_b32_e32 v7, 0, v59, vcc
	v_cndmask_b32_e32 v6, 0, v58, vcc
	v_cndmask_b32_e32 v5, 0, v57, vcc
	v_cndmask_b32_e32 v4, 0, v56, vcc
	v_lshlrev_b32_e32 v13, 16, v5
	v_lshlrev_b32_e32 v12, 16, v4
	v_and_b32_e32 v15, 0xffff0000, v5
	v_and_b32_e32 v14, 0xffff0000, v4
	v_and_b32_e32 v17, 0xffff0000, v6
	v_lshlrev_b32_e32 v16, 16, v6
	v_and_b32_e32 v19, 0xffff0000, v7
	v_lshlrev_b32_e32 v18, 16, v7
	ds_bpermute_b32 v26, v113, v12
	ds_bpermute_b32 v24, v113, v14
	ds_bpermute_b32 v27, v113, v13
	ds_bpermute_b32 v25, v113, v15
	ds_bpermute_b32 v22, v113, v16
	ds_bpermute_b32 v23, v113, v17
	ds_bpermute_b32 v20, v113, v18
	ds_bpermute_b32 v21, v113, v19
	s_and_saveexec_b64 s[18:19], s[46:47]
	s_waitcnt lgkmcnt(4)
	v_pk_mul_f32 v[24:25], v[88:89], v[24:25]
	s_waitcnt lgkmcnt(2)
	v_pk_mul_f32 v[22:23], v[88:89], v[22:23]
	s_waitcnt lgkmcnt(0)
	v_pk_mul_f32 v[20:21], v[88:89], v[20:21]
	v_pk_mul_f32 v[26:27], v[88:89], v[26:27]
	v_mov_b32_e32 v40, v210
	v_mov_b32_e32 v41, v212
	v_mov_b32_e32 v42, v218
	v_mov_b32_e32 v43, v220
	v_mov_b32_e32 v30, v219
	v_mov_b32_e32 v31, v221
	v_mov_b32_e32 v6, v211
	v_mov_b32_e32 v7, v213
	v_pk_mul_f32 v[4:5], v[22:23], v[224:225]
	v_pk_mul_f32 v[20:21], v[20:21], v[226:227]
	v_pk_mul_f32 v[24:25], v[24:25], v[30:31]
	v_pk_mul_f32 v[22:23], v[26:27], v[42:43]
	v_pk_fma_f32 v[4:5], v[214:215], v[16:17], v[4:5]
	v_pk_fma_f32 v[16:17], v[216:217], v[18:19], v[20:21]
	v_pk_fma_f32 v[6:7], v[6:7], v[14:15], v[24:25]
	v_pk_fma_f32 v[12:13], v[40:41], v[12:13], v[22:23]
	v_cvt_pk_bf16_f32 v14, v4, v5
	v_cvt_pk_bf16_f32 v5, v13, v7
	v_cvt_pk_bf16_f32 v4, v12, v6
	v_cvt_pk_bf16_f32 v7, v16, v17
	v_mov_b32_e32 v6, v14
	s_or_b64 exec, exec, s[18:19]
	ds_write_b128 v140, v[4:7]
	s_waitcnt vmcnt(10)
	v_add_u32_e32 v12, s51, v123
	v_cmp_gt_u32_e32 vcc, s37, v12
	s_nop 1
	v_cndmask_b32_e32 v7, 0, v63, vcc
	v_cndmask_b32_e32 v6, 0, v62, vcc
	v_cndmask_b32_e32 v5, 0, v61, vcc
	v_cndmask_b32_e32 v4, 0, v60, vcc
	v_lshlrev_b32_e32 v13, 16, v5
	v_lshlrev_b32_e32 v12, 16, v4
	v_and_b32_e32 v15, 0xffff0000, v5
	v_and_b32_e32 v14, 0xffff0000, v4
	v_and_b32_e32 v17, 0xffff0000, v6
	v_lshlrev_b32_e32 v16, 16, v6
	v_and_b32_e32 v19, 0xffff0000, v7
	v_lshlrev_b32_e32 v18, 16, v7
	ds_bpermute_b32 v26, v113, v12
	ds_bpermute_b32 v24, v113, v14
	ds_bpermute_b32 v27, v113, v13
	ds_bpermute_b32 v25, v113, v15
	ds_bpermute_b32 v22, v113, v16
	ds_bpermute_b32 v23, v113, v17
	ds_bpermute_b32 v20, v113, v18
	ds_bpermute_b32 v21, v113, v19
	s_and_saveexec_b64 s[18:19], s[46:47]
	s_waitcnt lgkmcnt(4)
	v_pk_mul_f32 v[24:25], v[88:89], v[24:25]
	s_waitcnt lgkmcnt(2)
	v_pk_mul_f32 v[22:23], v[88:89], v[22:23]
	s_waitcnt lgkmcnt(0)
	v_pk_mul_f32 v[20:21], v[88:89], v[20:21]
	v_pk_mul_f32 v[26:27], v[88:89], v[26:27]
	v_mov_b32_e32 v40, v228
	v_mov_b32_e32 v41, v230
	v_mov_b32_e32 v42, v236
	v_mov_b32_e32 v43, v238
	v_mov_b32_e32 v30, v237
	v_mov_b32_e32 v31, v239
	v_mov_b32_e32 v6, v229
	v_mov_b32_e32 v7, v231
	v_pk_mul_f32 v[4:5], v[22:23], v[172:173]
	v_pk_mul_f32 v[20:21], v[20:21], v[174:175]
	v_pk_mul_f32 v[24:25], v[24:25], v[30:31]
	v_pk_mul_f32 v[22:23], v[26:27], v[42:43]
	v_pk_fma_f32 v[4:5], v[232:233], v[16:17], v[4:5]
	v_pk_fma_f32 v[16:17], v[234:235], v[18:19], v[20:21]
	v_pk_fma_f32 v[6:7], v[6:7], v[14:15], v[24:25]
	v_pk_fma_f32 v[12:13], v[40:41], v[12:13], v[22:23]
	v_cvt_pk_bf16_f32 v14, v4, v5
	v_cvt_pk_bf16_f32 v5, v13, v7
	v_cvt_pk_bf16_f32 v4, v12, v6
	v_cvt_pk_bf16_f32 v7, v16, v17
	v_mov_b32_e32 v6, v14
	s_or_b64 exec, exec, s[18:19]
	ds_write_b128 v141, v[4:7]
	s_waitcnt vmcnt(6)
	v_add_u32_e32 v12, s51, v124
	v_cmp_gt_u32_e32 vcc, s37, v12
	s_nop 1
	v_cndmask_b32_e32 v7, 0, v67, vcc
	v_cndmask_b32_e32 v6, 0, v66, vcc
	v_cndmask_b32_e32 v5, 0, v65, vcc
	v_cndmask_b32_e32 v4, 0, v64, vcc
	v_lshlrev_b32_e32 v13, 16, v5
	v_lshlrev_b32_e32 v12, 16, v4
	v_and_b32_e32 v15, 0xffff0000, v5
	v_and_b32_e32 v14, 0xffff0000, v4
	v_and_b32_e32 v17, 0xffff0000, v6
	v_lshlrev_b32_e32 v16, 16, v6
	v_and_b32_e32 v19, 0xffff0000, v7
	v_lshlrev_b32_e32 v18, 16, v7
	ds_bpermute_b32 v26, v113, v12
	ds_bpermute_b32 v24, v113, v14
	ds_bpermute_b32 v27, v113, v13
	ds_bpermute_b32 v25, v113, v15
	ds_bpermute_b32 v22, v113, v16
	ds_bpermute_b32 v23, v113, v17
	ds_bpermute_b32 v20, v113, v18
	ds_bpermute_b32 v21, v113, v19
	s_and_saveexec_b64 s[18:19], s[46:47]
	s_waitcnt lgkmcnt(4)
	v_pk_mul_f32 v[24:25], v[88:89], v[24:25]
	s_waitcnt lgkmcnt(2)
	v_pk_mul_f32 v[22:23], v[88:89], v[22:23]
	s_waitcnt lgkmcnt(0)
	v_pk_mul_f32 v[20:21], v[88:89], v[20:21]
	v_pk_mul_f32 v[26:27], v[88:89], v[26:27]
	v_mov_b32_e32 v40, v68
	v_mov_b32_e32 v41, v70
	v_mov_b32_e32 v42, v76
	v_mov_b32_e32 v43, v78
	v_mov_b32_e32 v30, v77
	v_mov_b32_e32 v31, v79
	v_mov_b32_e32 v6, v69
	v_mov_b32_e32 v7, v71
	v_pk_mul_f32 v[4:5], v[22:23], v[80:81]
	v_pk_mul_f32 v[20:21], v[20:21], v[82:83]
	v_pk_mul_f32 v[24:25], v[24:25], v[30:31]
	v_pk_mul_f32 v[22:23], v[26:27], v[42:43]
	v_pk_fma_f32 v[4:5], v[72:73], v[16:17], v[4:5]
	v_pk_fma_f32 v[16:17], v[74:75], v[18:19], v[20:21]
	v_pk_fma_f32 v[6:7], v[6:7], v[14:15], v[24:25]
	v_pk_fma_f32 v[12:13], v[40:41], v[12:13], v[22:23]
	v_cvt_pk_bf16_f32 v14, v4, v5
	v_cvt_pk_bf16_f32 v5, v13, v7
	v_cvt_pk_bf16_f32 v4, v12, v6
	v_cvt_pk_bf16_f32 v7, v16, v17
	v_mov_b32_e32 v6, v14
	s_or_b64 exec, exec, s[18:19]
	ds_write_b128 v142, v[4:7]
	s_waitcnt vmcnt(5)
	v_add_u32_e32 v12, s51, v125
	v_cmp_gt_u32_e32 vcc, s37, v12
	s_nop 1
	v_cndmask_b32_e32 v4, 0, v44, vcc
	v_cndmask_b32_e32 v5, 0, v45, vcc
	v_cndmask_b32_e32 v6, 0, v46, vcc
	v_cndmask_b32_e32 v7, 0, v47, vcc
	ds_write_b16 v126, v4 offset:55296
	ds_write_b16_d16_hi v126, v4 offset:56080
	ds_write_b16 v126, v5 offset:56864
	ds_write_b16_d16_hi v126, v5 offset:57648
	ds_write_b16 v126, v6 offset:58432
	ds_write_b16_d16_hi v126, v6 offset:59216
	ds_write_b16 v126, v7 offset:60000
	ds_write_b16_d16_hi v126, v7 offset:60784
	s_waitcnt vmcnt(4)
	v_add_u32_e32 v12, s51, v127
	v_cmp_gt_u32_e32 vcc, s37, v12
	s_nop 1
	v_cndmask_b32_e32 v4, 0, v48, vcc
	v_cndmask_b32_e32 v5, 0, v49, vcc
	v_cndmask_b32_e32 v6, 0, v50, vcc
	v_cndmask_b32_e32 v7, 0, v51, vcc
	ds_write_b16 v128, v4 offset:56320
	ds_write_b16_d16_hi v128, v4 offset:57104
	ds_write_b16 v128, v5 offset:57888
	ds_write_b16_d16_hi v128, v5 offset:58672
	ds_write_b16 v128, v6 offset:59456
	ds_write_b16_d16_hi v128, v6 offset:60240
	ds_write_b16 v128, v7 offset:61024
	ds_write_b16_d16_hi v128, v7 offset:61808
	s_waitcnt vmcnt(3)
	v_add_u32_e32 v12, s51, v129
	v_cmp_gt_u32_e32 vcc, s37, v12
	s_nop 1
	v_cndmask_b32_e32 v4, 0, v176, vcc
	v_cndmask_b32_e32 v5, 0, v177, vcc
	v_cndmask_b32_e32 v6, 0, v178, vcc
	v_cndmask_b32_e32 v7, 0, v179, vcc
	ds_write_b16 v130, v4 offset:57344
	ds_write_b16_d16_hi v130, v4 offset:58128
	ds_write_b16 v130, v5 offset:58912
	ds_write_b16_d16_hi v130, v5 offset:59696
	ds_write_b16 v130, v6 offset:60480
	ds_write_b16_d16_hi v130, v6 offset:61264
	ds_write_b16 v130, v7 offset:62048
	ds_write_b16_d16_hi v130, v7 offset:62832
	s_waitcnt vmcnt(2)
	v_add_u32_e32 v12, s51, v131
	v_cmp_gt_u32_e32 vcc, s37, v12
	s_nop 1
	v_cndmask_b32_e32 v4, 0, v180, vcc
	v_cndmask_b32_e32 v5, 0, v181, vcc
	v_cndmask_b32_e32 v6, 0, v182, vcc
	v_cndmask_b32_e32 v7, 0, v183, vcc
	ds_write_b16 v132, v4 offset:58368
	ds_write_b16_d16_hi v132, v4 offset:59152
	ds_write_b16 v132, v5 offset:59936
	ds_write_b16_d16_hi v132, v5 offset:60720
	ds_write_b16 v132, v6 offset:61504
	ds_write_b16_d16_hi v132, v6 offset:62288
	ds_write_b16 v132, v7 offset:63072
	ds_write_b16_d16_hi v132, v7 offset:63856
	s_waitcnt vmcnt(1)
	v_add_u32_e32 v12, s51, v133
	v_cmp_gt_u32_e32 vcc, s37, v12
	s_nop 1
	v_cndmask_b32_e32 v4, 0, v184, vcc
	v_cndmask_b32_e32 v5, 0, v185, vcc
	v_cndmask_b32_e32 v6, 0, v186, vcc
	v_cndmask_b32_e32 v7, 0, v187, vcc
	ds_write_b16 v134, v4 offset:59392
	ds_write_b16_d16_hi v134, v4 offset:60176
	ds_write_b16 v134, v5 offset:60960
	ds_write_b16_d16_hi v134, v5 offset:61744
	ds_write_b16 v134, v6 offset:62528
	ds_write_b16_d16_hi v134, v6 offset:63312
	ds_write_b16 v134, v7 offset:64096
	ds_write_b16_d16_hi v134, v7 offset:64880
	s_waitcnt vmcnt(0)
	v_add_u32_e32 v12, s51, v135
	v_cmp_gt_u32_e32 vcc, s37, v12
	s_nop 1
	v_cndmask_b32_e32 v4, 0, v188, vcc
	v_cndmask_b32_e32 v5, 0, v189, vcc
	v_cndmask_b32_e32 v6, 0, v190, vcc
	v_cndmask_b32_e32 v7, 0, v191, vcc
	ds_write_b16 v136, v4 offset:60416
	ds_write_b16_d16_hi v136, v4 offset:61200
	ds_write_b16 v136, v5 offset:61984
	ds_write_b16_d16_hi v136, v5 offset:62768
	ds_write_b16 v136, v6 offset:63552
	ds_write_b16_d16_hi v136, v6 offset:64336
	ds_write_b16 v136, v7 offset:65120
	ds_write_b16_d16_hi v137, v7 offset:5488
	s_lshr_b32 s18, s45, 1
	s_and_b32 s18, s18, 63
	v_lshl_or_b32 v12, s18, 7, v112
	v_lshlrev_b32_e32 v152, 6, v12
	v_lshl_add_u64 v[108:109], s[12:13], 0, v[152:153]
	v_lshlrev_b32_e32 v152, 10, v12
	v_cndmask_b32_e64 v12, 0, 1, s[10:11]
	s_nop 1
	v_readfirstlane_b32 s18, v12
	s_nop 1
	s_lshl_b32 s18, s18, 8
	s_add_i32 s18, s44, s18
	s_ashr_i32 s19, s18, 31
	s_lshl_b64 s[18:19], s[18:19], 1
	s_ashr_i32 s17, s16, 31
	s_lshl_b64 s[16:17], s[16:17], 2
	v_readlane_b32 s8, v254, 0
	s_nop 1
	s_add_u32 s16, s8, s16
	v_readlane_b32 s8, v254, 1
	s_nop 1
	s_addc_u32 s17, s8, s17
	s_sub_i32 s60, 0x80, s50
	s_sub_i32 s61, 0x2080, s50
	s_lshl_b64 s[0:1], s[0:1], 23
	s_add_u32 s0, s18, s0
	s_addc_u32 s1, s19, s1
	s_mov_b32 s18, 0xd000
	s_mov_b32 s19, s21
	s_waitcnt lgkmcnt(0)
	s_barrier
	s_and_saveexec_b64 s[50:51], s[48:49]
	global_load_dwordx4 v[176:179], v[108:109], off
	global_load_dwordx4 v[180:183], v[108:109], off offset:32
	global_load_dwordx4 v[184:187], v[108:109], off offset:48
	global_load_dwordx4 v[188:191], v[108:109], off offset:16
	s_or_b64 exec, exec, s[50:51]
	global_load_dword v4, v153, s[16:17]
	s_mov_b64 s[16:17], 0
	s_waitcnt vmcnt(0)
	v_mul_f32_e32 v143, 0x3fb8aa3b, v4
	v_lshl_add_u64 v[4:5], s[0:1], 0, v[152:153]
	v_lshl_add_u64 v[110:111], v[104:105], 0, v[4:5]
	s_branch .LBB0_579
	.p2align	6
.LBB0_578:
	v_or_b32_e32 v16, 0x100, v80
	v_cmp_le_u32_e32 vcc, v80, v149
	v_cmp_gt_u32_e64 s[0:1], s61, v16
	s_and_b64 vcc, vcc, s[0:1]
	v_mul_f32_e32 v12, 0x3e38aa3b, v12
	v_or_b32_e32 v16, 0x104, v80
	v_cndmask_b32_e32 v12, v208, v12, vcc
	v_cmp_le_u32_e32 vcc, v16, v51
	v_cmp_gt_u32_e64 s[0:1], s61, v16
	s_and_b64 vcc, vcc, s[0:1]
	v_mul_f32_e32 v8, 0x3e38aa3b, v8
	v_or_b32_e32 v17, 0x101, v80
	v_cndmask_b32_e32 v8, v208, v8, vcc
	v_cmp_le_u32_e32 vcc, v17, v51
	v_cmp_gt_u32_e64 s[0:1], s61, v17
	s_and_b64 vcc, vcc, s[0:1]
	v_mul_f32_e32 v13, 0x3e38aa3b, v13
	v_or_b32_e32 v17, 0x105, v80
	v_cndmask_b32_e32 v13, v208, v13, vcc
	v_cmp_le_u32_e32 vcc, v17, v51
	v_cmp_gt_u32_e64 s[0:1], s61, v17
	s_and_b64 vcc, vcc, s[0:1]
	v_mul_f32_e32 v9, 0x3e38aa3b, v9
	v_cndmask_b32_e32 v149, v208, v9, vcc
	v_max_f32_e32 v16, v12, v8
	v_max_f32_e32 v9, v13, v149
	v_max3_f32 v9, v151, v16, v9
	v_or_b32_e32 v16, 0x102, v80
	v_cmp_le_u32_e32 vcc, v16, v51
	v_cmp_gt_u32_e64 s[0:1], s61, v16
	s_and_b64 vcc, vcc, s[0:1]
	v_mul_f32_e32 v14, 0x3e38aa3b, v14
	v_or_b32_e32 v16, 0x106, v80
	v_cndmask_b32_e32 v14, v208, v14, vcc
	v_cmp_le_u32_e32 vcc, v16, v51
	v_cmp_gt_u32_e64 s[0:1], s61, v16
	s_and_b64 vcc, vcc, s[0:1]
	v_mul_f32_e32 v10, 0x3e38aa3b, v10
	v_or_b32_e32 v16, 0x103, v80
	v_cndmask_b32_e32 v151, v208, v10, vcc
	v_cmp_le_u32_e32 vcc, v16, v51
	v_cmp_gt_u32_e64 s[0:1], s61, v16
	s_and_b64 vcc, vcc, s[0:1]
	v_mul_f32_e32 v15, 0x3e38aa3b, v15
	v_cndmask_b32_e32 v152, v208, v15, vcc
	v_or_b32_e32 v15, 0x107, v80
	v_cmp_le_u32_e32 vcc, v15, v51
	v_cmp_gt_u32_e64 s[0:1], s61, v15
	s_and_b64 vcc, vcc, s[0:1]
	v_mul_f32_e32 v11, 0x3e38aa3b, v11
	v_cndmask_b32_e32 v173, v208, v11, vcc
	v_max_f32_e32 v10, v14, v151
	v_max_f32_e32 v11, v152, v173
	v_max3_f32 v9, v9, v10, v11
	ds_bpermute_b32 v10, v114, v9
	s_waitcnt lgkmcnt(0)
	v_max_f32_e32 v10, v10, v10
	v_max_f32_e32 v9, v9, v10
	ds_bpermute_b32 v10, v117, v9
	s_waitcnt lgkmcnt(0)
	v_max_f32_e32 v10, v10, v10
	v_max_f32_e32 v172, v9, v10
	v_sub_f32_e32 v81, v81, v172
	v_exp_f32_e32 v81, v81
	v_pk_add_f32 v[82:83], v[82:83], v[172:173] op_sel_hi:[1,0] neg_lo:[0,1] neg_hi:[0,1]
	v_exp_f32_e32 v82, v82
	v_exp_f32_e32 v83, v83
	v_pk_add_f32 v[144:145], v[144:145], v[172:173] op_sel_hi:[1,0] neg_lo:[0,1] neg_hi:[0,1]
	v_exp_f32_e32 v144, v144
	v_add_f32_e32 v9, v81, v82
	v_add_f32_e32 v9, 0, v9
	v_sub_f32_e32 v8, v8, v172
	v_add_f32_e32 v10, v83, v144
	v_add_f32_e32 v9, v10, v9
	v_exp_f32_e32 v145, v145
	v_pk_add_f32 v[146:147], v[146:147], v[172:173] op_sel_hi:[1,0] neg_lo:[0,1] neg_hi:[0,1]
	v_exp_f32_e32 v146, v146
	s_nop 0
	v_add_f32_e32 v10, v145, v146
	v_add_f32_e32 v9, v10, v9
	v_exp_f32_e32 v147, v147
	v_pk_add_f32 v[148:149], v[148:149], v[172:173] op_sel_hi:[1,0] neg_lo:[0,1] neg_hi:[0,1]
	v_exp_f32_e32 v148, v148
	s_nop 0
	v_add_f32_e32 v10, v147, v148
	v_add_f32_e32 v9, v10, v9
	v_pk_add_f32 v[74:75], v[74:75], v[172:173] op_sel_hi:[1,0] neg_lo:[0,1] neg_hi:[0,1]
	v_exp_f32_e32 v51, v74
	v_pk_add_f32 v[72:73], v[72:73], v[172:173] op_sel_hi:[1,0] neg_lo:[0,1] neg_hi:[0,1]
	v_exp_f32_e32 v72, v72
	s_nop 0
	v_add_f32_e32 v10, v51, v72
	v_add_f32_e32 v9, v10, v9
	v_exp_f32_e32 v74, v75
	v_exp_f32_e32 v73, v73
	s_nop 0
	v_add_f32_e32 v10, v74, v73
	v_add_f32_e32 v9, v10, v9
	v_pk_add_f32 v[78:79], v[78:79], v[172:173] op_sel_hi:[1,0] neg_lo:[0,1] neg_hi:[0,1]
	v_exp_f32_e32 v75, v78
	v_pk_add_f32 v[76:77], v[76:77], v[172:173] op_sel_hi:[1,0] neg_lo:[0,1] neg_hi:[0,1]
	v_exp_f32_e32 v76, v76
	s_nop 0
	v_add_f32_e32 v10, v75, v76
	v_add_f32_e32 v9, v10, v9
	v_exp_f32_e32 v78, v79
	v_exp_f32_e32 v79, v77
	s_nop 0
	v_add_f32_e32 v10, v78, v79
	v_add_f32_e32 v9, v10, v9
	v_pk_add_f32 v[66:67], v[66:67], v[172:173] op_sel_hi:[1,0] neg_lo:[0,1] neg_hi:[0,1]
	v_exp_f32_e32 v66, v66
	v_pk_add_f32 v[64:65], v[64:65], v[172:173] op_sel_hi:[1,0] neg_lo:[0,1] neg_hi:[0,1]
	v_exp_f32_e32 v64, v64
	s_nop 0
	v_add_f32_e32 v10, v66, v64
	v_add_f32_e32 v9, v10, v9
	v_exp_f32_e32 v67, v67
	v_exp_f32_e32 v65, v65
	s_nop 0
	v_add_f32_e32 v10, v67, v65
	v_add_f32_e32 v9, v10, v9
	v_pk_add_f32 v[70:71], v[70:71], v[172:173] op_sel_hi:[1,0] neg_lo:[0,1] neg_hi:[0,1]
	v_exp_f32_e32 v70, v70
	v_pk_add_f32 v[68:69], v[68:69], v[172:173] op_sel_hi:[1,0] neg_lo:[0,1] neg_hi:[0,1]
	v_exp_f32_e32 v77, v68
	s_nop 0
	v_add_f32_e32 v10, v70, v77
	v_add_f32_e32 v9, v10, v9
	v_exp_f32_e32 v71, v71
	v_exp_f32_e32 v69, v69
	s_nop 0
	v_add_f32_e32 v10, v71, v69
	v_add_f32_e32 v9, v10, v9
	v_pk_add_f32 v[58:59], v[58:59], v[172:173] op_sel_hi:[1,0] neg_lo:[0,1] neg_hi:[0,1]
	v_exp_f32_e32 v58, v58
	v_pk_add_f32 v[56:57], v[56:57], v[172:173] op_sel_hi:[1,0] neg_lo:[0,1] neg_hi:[0,1]
	v_exp_f32_e32 v56, v56
	s_nop 0
	v_add_f32_e32 v10, v58, v56
	v_add_f32_e32 v9, v10, v9
	v_exp_f32_e32 v59, v59
	v_exp_f32_e32 v68, v57
	s_nop 0
	v_add_f32_e32 v10, v59, v68
	v_add_f32_e32 v9, v10, v9
	v_pk_add_f32 v[62:63], v[62:63], v[172:173] op_sel_hi:[1,0] neg_lo:[0,1] neg_hi:[0,1]
	v_exp_f32_e32 v62, v62
	v_pk_add_f32 v[60:61], v[60:61], v[172:173] op_sel_hi:[1,0] neg_lo:[0,1] neg_hi:[0,1]
	v_exp_f32_e32 v60, v60
	s_nop 0
	v_add_f32_e32 v10, v62, v60
	v_add_f32_e32 v9, v10, v9
	v_exp_f32_e32 v63, v63
	v_exp_f32_e32 v61, v61
	s_nop 0
	v_add_f32_e32 v10, v63, v61
	v_add_f32_e32 v9, v10, v9
	v_pk_add_f32 v[150:151], v[150:151], v[172:173] op_sel_hi:[1,0] neg_lo:[0,1] neg_hi:[0,1]
	v_exp_f32_e32 v57, v150
	v_pk_add_f32 v[54:55], v[54:55], v[172:173] op_sel_hi:[1,0] neg_lo:[0,1] neg_hi:[0,1]
	v_exp_f32_e32 v55, v55
	s_nop 0
	v_add_f32_e32 v10, v57, v55
	v_add_f32_e32 v9, v10, v9
	v_exp_f32_e32 v54, v54
	v_pk_add_f32 v[52:53], v[52:53], v[172:173] op_sel_hi:[1,0] neg_lo:[0,1] neg_hi:[0,1]
	v_exp_f32_e32 v53, v53
	s_nop 0
	v_add_f32_e32 v10, v54, v53
	v_add_f32_e32 v9, v10, v9
	v_exp_f32_e32 v52, v52
	v_sub_f32_e32 v50, v50, v172
	v_exp_f32_e32 v50, v50
	s_nop 0
	v_add_f32_e32 v10, v52, v50
	v_add_f32_e32 v9, v10, v9
	v_pk_add_f32 v[48:49], v[48:49], v[172:173] op_sel_hi:[1,0] neg_lo:[0,1] neg_hi:[0,1]
	v_exp_f32_e32 v49, v49
	v_exp_f32_e32 v48, v48
	s_nop 0
	v_add_f32_e32 v10, v49, v48
	v_add_f32_e32 v9, v10, v9
	v_pk_add_f32 v[42:43], v[42:43], v[172:173] op_sel_hi:[1,0] neg_lo:[0,1] neg_hi:[0,1]
	v_exp_f32_e32 v42, v42
	v_pk_add_f32 v[40:41], v[40:41], v[172:173] op_sel_hi:[1,0] neg_lo:[0,1] neg_hi:[0,1]
	v_exp_f32_e32 v40, v40
	s_nop 0
	v_add_f32_e32 v10, v42, v40
	v_add_f32_e32 v9, v10, v9
	v_exp_f32_e32 v43, v43
	v_exp_f32_e32 v41, v41
	s_nop 0
	v_add_f32_e32 v10, v43, v41
	v_add_f32_e32 v9, v10, v9
	v_pk_add_f32 v[46:47], v[46:47], v[172:173] op_sel_hi:[1,0] neg_lo:[0,1] neg_hi:[0,1]
	v_exp_f32_e32 v46, v46
	v_pk_add_f32 v[44:45], v[44:45], v[172:173] op_sel_hi:[1,0] neg_lo:[0,1] neg_hi:[0,1]
	v_exp_f32_e32 v44, v44
	s_nop 0
	v_add_f32_e32 v10, v46, v44
	v_add_f32_e32 v9, v10, v9
	v_exp_f32_e32 v47, v47
	v_exp_f32_e32 v45, v45
	s_nop 0
	v_add_f32_e32 v10, v47, v45
	v_add_f32_e32 v9, v10, v9
	v_pk_add_f32 v[34:35], v[34:35], v[172:173] op_sel_hi:[1,0] neg_lo:[0,1] neg_hi:[0,1]
	v_exp_f32_e32 v34, v34
	v_pk_add_f32 v[32:33], v[32:33], v[172:173] op_sel_hi:[1,0] neg_lo:[0,1] neg_hi:[0,1]
	v_exp_f32_e32 v32, v32
	s_nop 0
	v_add_f32_e32 v10, v34, v32
	v_add_f32_e32 v9, v10, v9
	v_exp_f32_e32 v35, v35
	v_exp_f32_e32 v33, v33
	s_nop 0
	v_add_f32_e32 v10, v35, v33
	v_add_f32_e32 v9, v10, v9
	v_pk_add_f32 v[38:39], v[38:39], v[172:173] op_sel_hi:[1,0] neg_lo:[0,1] neg_hi:[0,1]
	v_exp_f32_e32 v38, v38
	v_pk_add_f32 v[36:37], v[36:37], v[172:173] op_sel_hi:[1,0] neg_lo:[0,1] neg_hi:[0,1]
	v_exp_f32_e32 v36, v36
	s_nop 0
	v_add_f32_e32 v10, v38, v36
	v_add_f32_e32 v9, v10, v9
	v_exp_f32_e32 v39, v39
	v_exp_f32_e32 v37, v37
	s_nop 0
	v_add_f32_e32 v10, v39, v37
	v_add_f32_e32 v9, v10, v9
	v_pk_add_f32 v[26:27], v[26:27], v[172:173] op_sel_hi:[1,0] neg_lo:[0,1] neg_hi:[0,1]
	v_exp_f32_e32 v17, v26
	v_pk_add_f32 v[24:25], v[24:25], v[172:173] op_sel_hi:[1,0] neg_lo:[0,1] neg_hi:[0,1]
	v_exp_f32_e32 v19, v24
	v_exp_f32_e32 v16, v27
	v_exp_f32_e32 v18, v25
	s_nop 0
	v_pk_add_f32 v[10:11], v[16:17], v[18:19]
	s_nop 0
	v_add_f32_e32 v9, v11, v9
	v_add_f32_e32 v9, v10, v9
	v_pk_add_f32 v[30:31], v[30:31], v[172:173] op_sel_hi:[1,0] neg_lo:[0,1] neg_hi:[0,1]
	v_exp_f32_e32 v21, v30
	v_pk_add_f32 v[28:29], v[28:29], v[172:173] op_sel_hi:[1,0] neg_lo:[0,1] neg_hi:[0,1]
	v_exp_f32_e32 v23, v28
	v_exp_f32_e32 v20, v31
	v_exp_f32_e32 v22, v29
	v_cvt_pk_bf16_f32 v28, v81, v83
	v_cvt_pk_bf16_f32 v29, v145, v147
	v_cvt_pk_bf16_f32 v30, v82, v144
	v_cvt_pk_bf16_f32 v31, v146, v148
	s_nop 1
	s_nop 0
	v_pk_add_f32 v[10:11], v[20:21], v[22:23]
	s_nop 0
	v_add_f32_e32 v9, v11, v9
	v_add_f32_e32 v15, v10, v9
	v_pk_add_f32 v[12:13], v[12:13], v[172:173] op_sel_hi:[1,0] neg_lo:[0,1] neg_hi:[0,1]
	v_exp_f32_e32 v11, v8
	v_exp_f32_e32 v9, v12
	v_exp_f32_e32 v8, v13
	v_exp_f32_e32 v10, v149
	s_nop 0
	v_pk_add_f32 v[12:13], v[8:9], v[10:11]
	s_nop 0
	v_add_f32_e32 v13, v13, v15
	v_add_f32_e32 v26, v12, v13
	v_sub_f32_e32 v14, v14, v172
	v_exp_f32_e32 v13, v14
	v_exp_f32_e32 v15, v151
	v_sub_f32_e32 v152, v152, v172
	v_sub_f32_e32 v173, v173, v172
	v_exp_f32_e32 v12, v152
	v_exp_f32_e32 v14, v173
	s_nop 0
	v_pk_add_f32 v[24:25], v[12:13], v[14:15]
	s_nop 0
	v_add_f32_e32 v25, v25, v26
	v_add_f32_e32 v24, v24, v25
	ds_bpermute_b32 v25, v114, v24
	v_lshl_add_u32 v26, v80, 1, v118
	ds_read_b128 v[80:83], v26 offset:55296
	s_waitcnt lgkmcnt(1)
	v_add_f32_e32 v24, v24, v25
	ds_bpermute_b32 v25, v117, v24
	s_waitcnt lgkmcnt(0)
	v_add_f32_e32 v24, v24, v25
	v_sub_f32_e32 v25, v143, v172
	v_exp_f32_e32 v25, v25
	s_nop 0
	v_add_f32_e32 v24, v25, v24
	v_add_u32_e32 v25, 0xd800, v26
	ds_read_b128 v[144:147], v25 offset:12544
	ds_read_b128 v[172:175], v25 offset:37632
	ds_read_b128 v[148:151], v25 offset:25088
	v_mfma_f32_16x16x32_bf16 v[80:83], v[80:83], v[28:31], 0
	s_waitcnt lgkmcnt(2)
	v_mfma_f32_16x16x32_bf16 v[144:147], v[144:147], v[28:31], 0
	s_waitcnt lgkmcnt(0)
	v_mfma_f32_16x16x32_bf16 v[148:151], v[148:151], v[28:31], 0
	v_mfma_f32_16x16x32_bf16 v[28:31], v[172:175], v[28:31], 0
	v_cvt_pk_bf16_f32 v172, v51, v74
	v_cvt_pk_bf16_f32 v173, v75, v78
	v_cvt_pk_bf16_f32 v174, v72, v73
	v_cvt_pk_bf16_f32 v175, v76, v79
	s_nop 1
	ds_read_b128 v[72:75], v26 offset:55360
	s_waitcnt lgkmcnt(0)
	v_mfma_f32_16x16x32_bf16 v[72:75], v[72:75], v[172:175], v[80:83]
	s_nop 2
	ds_read_b128 v[78:81], v25 offset:12608
	s_waitcnt lgkmcnt(0)
	v_mfma_f32_16x16x32_bf16 v[78:81], v[78:81], v[172:175], v[144:147]
	s_nop 2
	ds_read_b128 v[144:147], v25 offset:25152
	s_waitcnt lgkmcnt(0)
	v_mfma_f32_16x16x32_bf16 v[144:147], v[144:147], v[172:175], v[148:151]
	s_nop 2
	ds_read_b128 v[148:151], v25 offset:37696
	s_waitcnt lgkmcnt(0)
	v_mfma_f32_16x16x32_bf16 v[28:31], v[148:151], v[172:175], v[28:31]
	v_cvt_pk_bf16_f32 v148, v66, v67
	v_cvt_pk_bf16_f32 v149, v70, v71
	v_cvt_pk_bf16_f32 v150, v64, v65
	v_cvt_pk_bf16_f32 v151, v77, v69
	s_nop 1
	ds_read_b128 v[64:67], v26 offset:55424
	s_waitcnt lgkmcnt(0)
	v_mfma_f32_16x16x32_bf16 v[64:67], v[64:67], v[148:151], v[72:75]
	s_nop 2
	ds_read_b128 v[70:73], v25 offset:12672
	ds_read_b128 v[74:77], v25 offset:25216
	s_waitcnt lgkmcnt(1)
	v_mfma_f32_16x16x32_bf16 v[70:73], v[70:73], v[148:151], v[78:81]
	s_nop 2
	ds_read_b128 v[78:81], v25 offset:37760
	s_waitcnt lgkmcnt(0)
	v_mfma_f32_16x16x32_bf16 v[28:31], v[78:81], v[148:151], v[28:31]
	v_cvt_pk_bf16_f32 v78, v58, v59
	v_cvt_pk_bf16_f32 v79, v62, v63
	v_cvt_pk_bf16_f32 v80, v56, v68
	v_cvt_pk_bf16_f32 v81, v60, v61
	s_nop 1
	ds_read_b128 v[58:61], v26 offset:55488
	s_waitcnt lgkmcnt(0)
	v_mfma_f32_16x16x32_bf16 v[58:61], v[58:61], v[78:81], v[64:67]
	s_nop 2
	ds_read_b128 v[62:65], v25 offset:12736
	ds_read_b128 v[66:69], v25 offset:25280
	s_waitcnt lgkmcnt(1)
	v_mfma_f32_16x16x32_bf16 v[62:65], v[62:65], v[78:81], v[70:73]
	s_nop 2
	ds_read_b128 v[70:73], v25 offset:37824
	s_waitcnt lgkmcnt(0)
	v_mfma_f32_16x16x32_bf16 v[28:31], v[70:73], v[78:81], v[28:31]
	v_cvt_pk_bf16_f32 v70, v57, v54
	v_cvt_pk_bf16_f32 v71, v52, v49
	v_cvt_pk_bf16_f32 v72, v55, v53
	v_cvt_pk_bf16_f32 v73, v50, v48
	s_nop 1
	ds_read_b128 v[48:51], v26 offset:55552
	ds_read_b128 v[52:55], v25 offset:12800
	s_waitcnt lgkmcnt(1)
	v_mfma_f32_16x16x32_bf16 v[48:51], v[48:51], v[70:73], v[58:61]
	s_nop 2
	ds_read_b128 v[56:59], v25 offset:25344
	s_waitcnt lgkmcnt(1)
	v_mfma_f32_16x16x32_bf16 v[52:55], v[52:55], v[70:73], v[62:65]
	s_nop 2
	ds_read_b128 v[60:63], v25 offset:37888
	s_waitcnt lgkmcnt(0)
	v_mfma_f32_16x16x32_bf16 v[28:31], v[60:63], v[70:73], v[28:31]
	v_cvt_pk_bf16_f32 v60, v42, v43
	v_cvt_pk_bf16_f32 v61, v46, v47
	v_cvt_pk_bf16_f32 v62, v40, v41
	v_cvt_pk_bf16_f32 v63, v44, v45
	s_nop 1
	ds_read_b128 v[40:43], v26 offset:55616
	ds_read_b128 v[44:47], v25 offset:12864
	s_waitcnt lgkmcnt(1)
	v_mfma_f32_16x16x32_bf16 v[40:43], v[40:43], v[60:63], v[48:51]
	s_nop 2
	ds_read_b128 v[48:51], v25 offset:25408
	s_waitcnt lgkmcnt(1)
	v_mfma_f32_16x16x32_bf16 v[44:47], v[44:47], v[60:63], v[52:55]
	s_nop 2
	ds_read_b128 v[52:55], v25 offset:37952
	s_waitcnt lgkmcnt(0)
	v_mfma_f32_16x16x32_bf16 v[28:31], v[52:55], v[60:63], v[28:31]
	v_cvt_pk_bf16_f32 v52, v34, v35
	v_cvt_pk_bf16_f32 v53, v38, v39
	v_cvt_pk_bf16_f32 v54, v32, v33
	v_cvt_pk_bf16_f32 v55, v36, v37
	s_nop 1
	ds_read_b128 v[32:35], v26 offset:55680
	ds_read_b128 v[36:39], v25 offset:12928
	s_waitcnt lgkmcnt(1)
	v_mfma_f32_16x16x32_bf16 v[32:35], v[32:35], v[52:55], v[40:43]
	s_nop 2
	ds_read_b128 v[40:43], v25 offset:25472
	s_waitcnt lgkmcnt(1)
	v_mfma_f32_16x16x32_bf16 v[36:39], v[36:39], v[52:55], v[44:47]
	s_nop 2
	ds_read_b128 v[44:47], v25 offset:38016
	s_waitcnt lgkmcnt(0)
	v_mfma_f32_16x16x32_bf16 v[28:31], v[44:47], v[52:55], v[28:31]
	v_cvt_pk_bf16_f32 v44, v17, v16
	v_cvt_pk_bf16_f32 v45, v21, v20
	v_cvt_pk_bf16_f32 v46, v19, v18
	v_cvt_pk_bf16_f32 v47, v23, v22
	s_nop 1
	ds_read_b128 v[16:19], v26 offset:55744
	ds_read_b128 v[20:23], v25 offset:12992
	s_waitcnt lgkmcnt(1)
	v_mfma_f32_16x16x32_bf16 v[16:19], v[16:19], v[44:47], v[32:35]
	s_nop 2
	ds_read_b128 v[32:35], v25 offset:25536
	s_waitcnt lgkmcnt(1)
	v_mfma_f32_16x16x32_bf16 v[20:23], v[20:23], v[44:47], v[36:39]
	s_nop 2
	ds_read_b128 v[36:39], v25 offset:38080
	s_waitcnt lgkmcnt(0)
	v_mfma_f32_16x16x32_bf16 v[28:31], v[36:39], v[44:47], v[28:31]
	v_cvt_pk_bf16_f32 v36, v9, v8
	v_cvt_pk_bf16_f32 v37, v13, v12
	v_cvt_pk_bf16_f32 v38, v11, v10
	v_cvt_pk_bf16_f32 v39, v15, v14
	s_nop 1
	ds_read_b128 v[8:11], v26 offset:55808
	ds_read_b128 v[12:15], v25 offset:13056
	s_waitcnt lgkmcnt(1)
	v_mfma_f32_16x16x32_bf16 v[8:11], v[8:11], v[36:39], v[16:19]
	s_nop 2
	ds_read_b128 v[16:19], v25 offset:25600
	s_waitcnt lgkmcnt(1)
	v_mfma_f32_16x16x32_bf16 v[12:15], v[12:15], v[36:39], v[20:23]
	s_nop 2
	ds_read_b128 v[20:23], v25 offset:38144
	v_div_scale_f32 v25, s[0:1], v24, v24, 1.0
	v_mfma_f32_16x16x32_bf16 v[74:77], v[74:77], v[148:151], v[144:147]
	v_rcp_f32_e32 v26, v25
	s_mov_b32 s0, 0x1b400000
	v_fma_f32 v27, -v25, v26, 1.0
	v_mfma_f32_16x16x32_bf16 v[66:69], v[66:69], v[78:81], v[74:77]
	v_fmac_f32_e32 v26, v27, v26
	v_div_scale_f32 v27, vcc, 1.0, v24, 1.0
	s_waitcnt lgkmcnt(0)
	v_mfma_f32_16x16x32_bf16 v[20:23], v[20:23], v[36:39], v[28:31]
	s_nop 2
	v_mul_f32_e32 v28, v27, v26
	v_fma_f32 v29, -v25, v28, v27
	v_mfma_f32_16x16x32_bf16 v[56:59], v[56:59], v[70:73], v[66:69]
	v_fmac_f32_e32 v28, v29, v26
	v_fma_f32 v25, -v25, v28, v27
	v_div_fmas_f32 v25, v25, v26, v28
	v_div_fixup_f32 v24, v25, v24, 1.0
	v_mfma_f32_16x16x32_bf16 v[48:51], v[48:51], v[60:63], v[56:59]
	v_mul_f32_e64 v8, v24, v8
	v_mul_f32_e64 v9, v24, v9
	v_pk_mul_f32 v[10:11], v[24:25], v[10:11] op_sel_hi:[0,1]
	v_cvt_pk_bf16_f32 v8, v8, v9
	s_nop 3
	v_mfma_f32_16x16x32_bf16 v[40:43], v[40:43], v[52:55], v[48:51]
	v_cvt_pk_bf16_f32 v9, v10, v11
	v_lshl_add_u64 v[26:27], v[110:111], 0, s[16:17]
	v_add_co_u32_e32 v10, vcc, s0, v26
	s_nop 5
	v_mfma_f32_16x16x32_bf16 v[32:35], v[32:35], v[44:47], v[40:43]
	s_nop 0
	v_addc_co_u32_e32 v11, vcc, 0, v27, vcc
	v_pk_mul_f32 v[12:13], v[24:25], v[12:13] op_sel_hi:[0,1]
	global_store_dwordx2 v[10:11], v[8:9], off
	v_pk_mul_f32 v[8:9], v[24:25], v[14:15] op_sel_hi:[0,1]
	v_cvt_pk_bf16_f32 v12, v12, v13
	s_nop 3
	v_mfma_f32_16x16x32_bf16 v[16:19], v[16:19], v[36:39], v[32:35]
	v_cvt_pk_bf16_f32 v13, v8, v9
	global_store_dwordx2 v[10:11], v[12:13], off offset:32
	s_nop 5
	v_pk_mul_f32 v[12:13], v[24:25], v[16:17] op_sel_hi:[0,1]
	v_cvt_pk_bf16_f32 v12, v12, v13
	v_pk_mul_f32 v[8:9], v[24:25], v[18:19] op_sel_hi:[0,1]
	v_cvt_pk_bf16_f32 v13, v8, v9
	global_store_dwordx2 v[10:11], v[12:13], off offset:64
	v_pk_mul_f32 v[12:13], v[24:25], v[20:21] op_sel_hi:[0,1]
	v_cvt_pk_bf16_f32 v12, v12, v13
	v_pk_mul_f32 v[8:9], v[24:25], v[22:23] op_sel_hi:[0,1]
	v_cvt_pk_bf16_f32 v13, v8, v9
	s_add_u32 s16, s16, 0x4000
	global_store_dwordx2 v[10:11], v[12:13], off offset:96
	s_addc_u32 s17, s17, 0
	s_add_i32 s18, s18, 0xd000
	s_add_i32 s19, s19, 16
	s_mov_b64 s[0:1], 0x400
	s_waitcnt vmcnt(4)
	v_mov_b64_e32 v[10:11], v[6:7]
	v_lshl_add_u64 v[108:109], v[108:109], 0, s[0:1]
	s_cmp_eq_u32 s16, 0x10000
	v_mov_b64_e32 v[8:9], v[4:5]
	s_cbranch_scc1 .LBB0_564
	.p2align	6

.LBB0_611:
	v_readlane_b32 s0, v253, 13
	v_readlane_b32 s1, v253, 14
	v_readlane_b32 s60, v253, 55
	s_andn2_b64 vcc, exec, s[0:1]
	v_readlane_b32 s0, v253, 48
	v_readlane_b32 s8, v253, 47
	v_readlane_b32 s61, v253, 56
	s_waitcnt vmcnt(0) lgkmcnt(0)
	s_barrier
	s_cbranch_vccnz .LBB0_615
	.p2align	6
.LBB0_612:
	s_ashr_i32 s1, s0, 31
	s_lshl_b64 s[10:11], s[0:1], 10
	s_add_u32 s10, s34, s10
	s_addc_u32 s11, s35, s11
	s_bfe_u32 s16, s0, 0x90004
	s_and_b32 s17, s0, 0xffffe000
	s_lshl_b32 s1, s16, 4
	s_mul_i32 s16, s16, 0x1a000
	s_mul_hi_i32 s18, s17, 0x1a00
	s_mulk_i32 s17, 0x1a00
	s_add_u32 s16, s16, s17
	s_addc_u32 s17, 0, s18
	s_add_u32 s16, s34, s16
	s_addc_u32 s17, s35, s17
	s_lshl_b32 s18, s8, 4
	s_and_b32 s20, s18, 0x1ff0
	v_sub_u32_e32 v0, s20, v200
	s_and_b32 s21, s18, 0xffffe000
	v_mad_i64_i32 v[144:145], vcc, s21, v207, v[170:171]
	v_mov_b32_e32 v141, s20
	v_mov_b32_e32 v143, 0
	v_add_u32_e32 v140, 0, v0
	v_cmp_gt_u32_e32 vcc, s37, v140
	s_nop 1
	v_cndmask_b32_e32 v140, v141, v140, vcc
	v_mul_i32_i24_e32 v142, 0xd00, v140
	v_lshl_add_u64 v[146:147], v[142:143], 1, v[144:145]
	global_load_dwordx4 v[76:79], v[146:147], off offset:1536
	v_add_u32_e32 v140, 1, v0
	v_cmp_gt_u32_e32 vcc, s37, v140
	s_nop 1
	v_cndmask_b32_e32 v140, v141, v140, vcc
	v_mul_i32_i24_e32 v142, 0xd00, v140
	v_lshl_add_u64 v[146:147], v[142:143], 1, v[144:145]
	global_load_dwordx4 v[80:83], v[146:147], off offset:1536
	v_add_u32_e32 v140, 2, v0
	v_cmp_gt_u32_e32 vcc, s37, v140
	s_and_b64 vcc, s[38:39], vcc
	s_nop 1
	v_cndmask_b32_e32 v140, v141, v140, vcc
	v_mul_i32_i24_e32 v142, 0xd00, v140
	v_lshl_add_u64 v[146:147], v[142:143], 1, v[144:145]
	global_load_dwordx4 v[84:87], v[146:147], off offset:1536
	v_add_u32_e32 v140, 3, v0
	v_cmp_gt_u32_e32 vcc, s37, v140
	s_and_b64 vcc, s[38:39], vcc
	s_nop 1
	v_cndmask_b32_e32 v140, v141, v140, vcc
	v_mul_i32_i24_e32 v142, 0xd00, v140
	v_lshl_add_u64 v[146:147], v[142:143], 1, v[144:145]
	global_load_dwordx4 v[88:91], v[146:147], off offset:1536
	v_add_u32_e32 v140, 4, v0
	v_cmp_gt_u32_e32 vcc, s37, v140
	s_and_b64 vcc, s[40:41], vcc
	s_nop 1
	v_cndmask_b32_e32 v140, v141, v140, vcc
	v_mul_i32_i24_e32 v142, 0xd00, v140
	v_lshl_add_u64 v[146:147], v[142:143], 1, v[144:145]
	global_load_dwordx4 v[92:95], v[146:147], off offset:1536
	v_add_u32_e32 v140, 5, v0
	v_cmp_gt_u32_e32 vcc, s37, v140
	s_and_b64 vcc, s[40:41], vcc
	s_nop 1
	v_cndmask_b32_e32 v140, v141, v140, vcc
	v_mul_i32_i24_e32 v142, 0xd00, v140
	v_lshl_add_u64 v[146:147], v[142:143], 1, v[144:145]
	global_load_dwordx4 v[96:99], v[146:147], off offset:1536
	v_add_u32_e32 v140, 6, v0
	v_cmp_gt_u32_e32 vcc, s37, v140
	s_and_b64 vcc, s[40:41], vcc
	s_nop 1
	v_cndmask_b32_e32 v140, v141, v140, vcc
	v_mul_i32_i24_e32 v142, 0xd00, v140
	v_lshl_add_u64 v[146:147], v[142:143], 1, v[144:145]
	global_load_dwordx4 v[100:103], v[146:147], off offset:1536
	v_add_u32_e32 v140, 7, v0
	v_cmp_gt_u32_e32 vcc, s37, v140
	s_and_b64 vcc, s[40:41], vcc
	s_nop 1
	v_cndmask_b32_e32 v140, v141, v140, vcc
	v_mul_i32_i24_e32 v142, 0xd00, v140
	v_lshl_add_u64 v[146:147], v[142:143], 1, v[144:145]
	global_load_dwordx4 v[104:107], v[146:147], off offset:1536
	v_add_u32_e32 v140, 8, v0
	v_cndmask_b32_e64 v140, v141, v140, s[42:43]
	v_mul_i32_i24_e32 v142, 0xd00, v140
	v_lshl_add_u64 v[146:147], v[142:143], 1, v[144:145]
	global_load_dwordx4 v[108:111], v[146:147], off offset:1536
	v_add_u32_e32 v140, 9, v0
	v_cndmask_b32_e64 v140, v141, v140, s[42:43]
	v_mul_i32_i24_e32 v142, 0xd00, v140
	v_lshl_add_u64 v[146:147], v[142:143], 1, v[144:145]
	global_load_dwordx4 v[112:115], v[146:147], off offset:1536
	v_add_u32_e32 v140, 10, v0
	v_cndmask_b32_e64 v140, v141, v140, s[42:43]
	v_mul_i32_i24_e32 v142, 0xd00, v140
	v_lshl_add_u64 v[146:147], v[142:143], 1, v[144:145]
	global_load_dwordx4 v[116:119], v[146:147], off offset:1536
	v_add_u32_e32 v140, 11, v0
	v_cndmask_b32_e64 v140, v141, v140, s[42:43]
	v_mul_i32_i24_e32 v142, 0xd00, v140
	v_lshl_add_u64 v[146:147], v[142:143], 1, v[144:145]
	global_load_dwordx4 v[120:123], v[146:147], off offset:1536
	v_add_u32_e32 v140, 12, v0
	v_cndmask_b32_e64 v140, v141, v140, s[42:43]
	v_mul_i32_i24_e32 v142, 0xd00, v140
	v_lshl_add_u64 v[146:147], v[142:143], 1, v[144:145]
	global_load_dwordx4 v[124:127], v[146:147], off offset:1536
	v_add_u32_e32 v140, 13, v0
	v_cndmask_b32_e64 v140, v141, v140, s[42:43]
	v_mul_i32_i24_e32 v142, 0xd00, v140
	v_lshl_add_u64 v[146:147], v[142:143], 1, v[144:145]
	global_load_dwordx4 v[128:131], v[146:147], off offset:1536
	v_add_u32_e32 v140, 14, v0
	v_cndmask_b32_e64 v140, v141, v140, s[42:43]
	v_mul_i32_i24_e32 v142, 0xd00, v140
	v_lshl_add_u64 v[146:147], v[142:143], 1, v[144:145]
	global_load_dwordx4 v[132:135], v[146:147], off offset:1536
	v_add_u32_e32 v140, 15, v0
	v_cndmask_b32_e64 v140, v141, v140, s[42:43]
	v_mul_i32_i24_e32 v142, 0xd00, v140
	v_lshl_add_u64 v[146:147], v[142:143], 1, v[144:145]
	global_load_dwordx4 v[136:139], v[146:147], off offset:1536
	s_waitcnt vmcnt(0)
	v_cmp_gt_u32_e32 vcc, s37, v0
	v_mov_b32_e32 v1, s20
	s_and_b32 s19, s18, 0xffffe000
	v_cndmask_b32_e32 v2, v1, v0, vcc
	v_mad_i64_i32 v[16:17], s[18:19], s19, v207, v[170:171]
	v_mul_i32_i24_e32 v152, 0xd00, v2
	v_lshl_add_u64 v[2:3], v[152:153], 1, v[16:17]
	v_mov_b32_e32 v2, v76
	v_mov_b32_e32 v3, v77
	v_mov_b32_e32 v4, v78
	v_mov_b32_e32 v5, v79
	v_or_b32_e32 v38, s1, v200
	v_add_u32_e32 v39, s1, v201
	s_mov_b32 s18, -4
	s_waitcnt vmcnt(0)
	v_cndmask_b32_e32 v8, 0, v2, vcc
	v_add_u32_e32 v2, 1, v0
	v_cndmask_b32_e32 v12, 0, v5, vcc
	v_cndmask_b32_e32 v6, 0, v4, vcc
	v_cndmask_b32_e32 v7, 0, v3, vcc
	v_cmp_gt_u32_e32 vcc, s37, v2
	s_nop 1
	v_cndmask_b32_e32 v2, v1, v2, vcc
	v_mul_i32_i24_e32 v152, 0xd00, v2
	v_lshl_add_u64 v[2:3], v[152:153], 1, v[16:17]
	v_mov_b32_e32 v2, v80
	v_mov_b32_e32 v3, v81
	v_mov_b32_e32 v4, v82
	v_mov_b32_e32 v5, v83
	s_waitcnt vmcnt(0)
	v_cndmask_b32_e32 v10, 0, v2, vcc
	v_add_u32_e32 v2, 2, v0
	v_cndmask_b32_e32 v13, 0, v5, vcc
	v_cndmask_b32_e32 v14, 0, v4, vcc
	v_cndmask_b32_e32 v9, 0, v3, vcc
	v_cmp_gt_u32_e32 vcc, s37, v2
	s_and_b64 vcc, s[38:39], vcc
	s_nop 0
	v_cndmask_b32_e32 v2, v1, v2, vcc
	v_mul_i32_i24_e32 v152, 0xd00, v2
	v_lshl_add_u64 v[2:3], v[152:153], 1, v[16:17]
	v_mov_b32_e32 v2, v84
	v_mov_b32_e32 v3, v85
	v_mov_b32_e32 v4, v86
	v_mov_b32_e32 v5, v87
	s_waitcnt vmcnt(0)
	v_cndmask_b32_e32 v11, 0, v2, vcc
	v_add_u32_e32 v2, 3, v0
	v_cndmask_b32_e32 v15, 0, v5, vcc
	v_cndmask_b32_e32 v18, 0, v4, vcc
	v_cndmask_b32_e32 v19, 0, v3, vcc
	v_cmp_gt_u32_e32 vcc, s37, v2
	s_and_b64 vcc, s[38:39], vcc
	s_nop 0
	v_cndmask_b32_e32 v2, v1, v2, vcc
	v_mul_i32_i24_e32 v152, 0xd00, v2
	v_lshl_add_u64 v[2:3], v[152:153], 1, v[16:17]
	v_mov_b32_e32 v2, v88
	v_mov_b32_e32 v3, v89
	v_mov_b32_e32 v4, v90
	v_mov_b32_e32 v5, v91
	s_waitcnt vmcnt(0)
	v_cndmask_b32_e32 v23, 0, v2, vcc
	v_add_u32_e32 v2, 4, v0
	v_cndmask_b32_e32 v20, 0, v5, vcc
	v_cndmask_b32_e32 v21, 0, v4, vcc
	v_cndmask_b32_e32 v22, 0, v3, vcc
	v_cmp_gt_u32_e32 vcc, s37, v2
	s_and_b64 vcc, s[40:41], vcc
	s_nop 0
	v_cndmask_b32_e32 v2, v1, v2, vcc
	v_mul_i32_i24_e32 v152, 0xd00, v2
	v_lshl_add_u64 v[2:3], v[152:153], 1, v[16:17]
	v_mov_b32_e32 v2, v92
	v_mov_b32_e32 v3, v93
	v_mov_b32_e32 v4, v94
	v_mov_b32_e32 v5, v95
	s_waitcnt vmcnt(0)
	v_cndmask_b32_e32 v26, 0, v3, vcc
	v_cndmask_b32_e32 v27, 0, v2, vcc
	v_lshlrev_b32_e32 v2, 16, v8
	v_and_b32_e32 v3, 0xffff0000, v8
	v_cndmask_b32_e32 v24, 0, v5, vcc
	v_cndmask_b32_e32 v25, 0, v4, vcc
	v_pk_add_f32 v[2:3], v[2:3], 0 op_sel_hi:[1,0]
	v_lshlrev_b32_e32 v4, 16, v10
	v_and_b32_e32 v5, 0xffff0000, v10
	v_pk_add_f32 v[2:3], v[2:3], v[4:5]
	v_lshlrev_b32_e32 v4, 16, v11
	v_and_b32_e32 v5, 0xffff0000, v11
	v_pk_add_f32 v[2:3], v[2:3], v[4:5]
	v_lshlrev_b32_e32 v4, 16, v23
	v_and_b32_e32 v5, 0xffff0000, v23
	v_pk_add_f32 v[2:3], v[2:3], v[4:5]
	v_lshlrev_b32_e32 v4, 16, v27
	v_and_b32_e32 v5, 0xffff0000, v27
	v_pk_add_f32 v[10:11], v[2:3], v[4:5]
	v_lshlrev_b32_e32 v2, 16, v7
	v_and_b32_e32 v3, 0xffff0000, v7
	v_pk_add_f32 v[2:3], v[2:3], 0 op_sel_hi:[1,0]
	v_lshlrev_b32_e32 v4, 16, v9
	v_and_b32_e32 v5, 0xffff0000, v9
	v_pk_add_f32 v[2:3], v[2:3], v[4:5]
	v_lshlrev_b32_e32 v4, 16, v19
	v_and_b32_e32 v5, 0xffff0000, v19
	v_pk_add_f32 v[2:3], v[2:3], v[4:5]
	v_lshlrev_b32_e32 v4, 16, v22
	v_and_b32_e32 v5, 0xffff0000, v22
	v_pk_add_f32 v[2:3], v[2:3], v[4:5]
	v_lshlrev_b32_e32 v4, 16, v26
	v_and_b32_e32 v5, 0xffff0000, v26
	v_pk_add_f32 v[8:9], v[2:3], v[4:5]
	v_lshlrev_b32_e32 v2, 16, v6
	v_and_b32_e32 v3, 0xffff0000, v6
	v_pk_add_f32 v[2:3], v[2:3], 0 op_sel_hi:[1,0]
	v_lshlrev_b32_e32 v4, 16, v14
	v_and_b32_e32 v5, 0xffff0000, v14
	v_pk_add_f32 v[2:3], v[2:3], v[4:5]
	v_lshlrev_b32_e32 v4, 16, v18
	v_and_b32_e32 v5, 0xffff0000, v18
	v_pk_add_f32 v[2:3], v[2:3], v[4:5]
	v_lshlrev_b32_e32 v4, 16, v21
	v_and_b32_e32 v5, 0xffff0000, v21
	v_pk_add_f32 v[2:3], v[2:3], v[4:5]
	v_lshlrev_b32_e32 v4, 16, v25
	v_and_b32_e32 v5, 0xffff0000, v25
	v_pk_add_f32 v[6:7], v[2:3], v[4:5]
	v_lshlrev_b32_e32 v2, 16, v12
	v_and_b32_e32 v3, 0xffff0000, v12
	v_pk_add_f32 v[2:3], v[2:3], 0 op_sel_hi:[1,0]
	v_lshlrev_b32_e32 v4, 16, v13
	v_and_b32_e32 v5, 0xffff0000, v13
	v_pk_add_f32 v[2:3], v[2:3], v[4:5]
	v_lshlrev_b32_e32 v4, 16, v15
	v_and_b32_e32 v5, 0xffff0000, v15
	v_pk_add_f32 v[2:3], v[2:3], v[4:5]
	v_lshlrev_b32_e32 v4, 16, v20
	v_and_b32_e32 v5, 0xffff0000, v20
	v_pk_add_f32 v[2:3], v[2:3], v[4:5]
	v_lshlrev_b32_e32 v4, 16, v24
	v_and_b32_e32 v5, 0xffff0000, v24
	v_pk_add_f32 v[4:5], v[2:3], v[4:5]
	v_add_u32_e32 v2, 5, v0
	v_cmp_gt_u32_e32 vcc, s37, v2
	s_and_b64 vcc, s[40:41], vcc
	s_nop 0
	v_cndmask_b32_e32 v2, v1, v2, vcc
	v_mul_i32_i24_e32 v152, 0xd00, v2
	v_lshl_add_u64 v[2:3], v[152:153], 1, v[16:17]
	v_mov_b32_e32 v12, v96
	v_mov_b32_e32 v13, v97
	v_mov_b32_e32 v14, v98
	v_mov_b32_e32 v15, v99
	s_waitcnt vmcnt(0)
	v_cndmask_b32_e32 v2, 0, v15, vcc
	v_cndmask_b32_e32 v13, 0, v13, vcc
	v_cndmask_b32_e32 v12, 0, v12, vcc
	v_lshlrev_b32_e32 v20, 16, v12
	v_and_b32_e32 v21, 0xffff0000, v12
	v_lshlrev_b32_e32 v18, 16, v13
	v_and_b32_e32 v19, 0xffff0000, v13
	v_lshlrev_b32_e32 v12, 16, v2
	v_and_b32_e32 v13, 0xffff0000, v2
	v_add_u32_e32 v2, 6, v0
	v_cndmask_b32_e32 v3, 0, v14, vcc
	v_cmp_gt_u32_e32 vcc, s37, v2
	s_and_b64 vcc, s[40:41], vcc
	v_lshlrev_b32_e32 v14, 16, v3
	v_cndmask_b32_e32 v2, v1, v2, vcc
	v_mul_i32_i24_e32 v152, 0xd00, v2
	v_and_b32_e32 v15, 0xffff0000, v3
	v_lshl_add_u64 v[2:3], v[152:153], 1, v[16:17]
	v_mov_b32_e32 v22, v100
	v_mov_b32_e32 v23, v101
	v_mov_b32_e32 v24, v102
	v_mov_b32_e32 v25, v103
	v_pk_add_f32 v[8:9], v[8:9], v[18:19]
	v_pk_add_f32 v[6:7], v[6:7], v[14:15]
	v_pk_add_f32 v[4:5], v[4:5], v[12:13]
	s_waitcnt vmcnt(0)
	v_cndmask_b32_e32 v2, 0, v25, vcc
	v_cndmask_b32_e32 v23, 0, v23, vcc
	v_cndmask_b32_e32 v22, 0, v22, vcc
	v_lshlrev_b32_e32 v32, 16, v22
	v_and_b32_e32 v33, 0xffff0000, v22
	v_lshlrev_b32_e32 v28, 16, v23
	v_and_b32_e32 v29, 0xffff0000, v23
	v_lshlrev_b32_e32 v22, 16, v2
	v_and_b32_e32 v23, 0xffff0000, v2
	v_add_u32_e32 v2, 7, v0
	v_cndmask_b32_e32 v3, 0, v24, vcc
	v_cmp_gt_u32_e32 vcc, s37, v2
	s_and_b64 vcc, s[40:41], vcc
	v_lshlrev_b32_e32 v24, 16, v3
	v_cndmask_b32_e32 v2, v1, v2, vcc
	v_mul_i32_i24_e32 v152, 0xd00, v2
	v_and_b32_e32 v25, 0xffff0000, v3
	v_lshl_add_u64 v[2:3], v[152:153], 1, v[16:17]
	v_mov_b32_e32 v34, v104
	v_mov_b32_e32 v35, v105
	v_mov_b32_e32 v36, v106
	v_mov_b32_e32 v37, v107
	v_pk_add_f32 v[8:9], v[8:9], v[28:29]
	v_pk_add_f32 v[6:7], v[6:7], v[24:25]
	v_pk_add_f32 v[4:5], v[4:5], v[22:23]
	s_waitcnt vmcnt(0)
	v_cndmask_b32_e32 v2, 0, v37, vcc
	v_cndmask_b32_e32 v26, 0, v35, vcc
	v_cndmask_b32_e32 v27, 0, v34, vcc
	v_cndmask_b32_e32 v3, 0, v36, vcc
	v_lshlrev_b32_e32 v36, 16, v27
	v_and_b32_e32 v37, 0xffff0000, v27
	v_lshlrev_b32_e32 v34, 16, v26
	v_and_b32_e32 v35, 0xffff0000, v26
	v_lshlrev_b32_e32 v26, 16, v2
	v_and_b32_e32 v27, 0xffff0000, v2
	v_add_u32_e32 v2, 8, v0
	v_cndmask_b32_e64 v2, v1, v2, s[42:43]
	v_mul_i32_i24_e32 v152, 0xd00, v2
	v_lshlrev_b32_e32 v30, 16, v3
	v_and_b32_e32 v31, 0xffff0000, v3
	v_lshl_add_u64 v[2:3], v[152:153], 1, v[16:17]
	v_mov_b32_e32 v44, v108
	v_mov_b32_e32 v45, v109
	v_mov_b32_e32 v46, v110
	v_mov_b32_e32 v47, v111
	v_add_u32_e32 v2, 9, v0
	v_cndmask_b32_e64 v2, v1, v2, s[42:43]
	v_mul_i32_i24_e32 v152, 0xd00, v2
	v_lshl_add_u64 v[2:3], v[152:153], 1, v[16:17]
	v_mov_b32_e32 v48, v112
	v_mov_b32_e32 v49, v113
	v_mov_b32_e32 v50, v114
	v_mov_b32_e32 v51, v115
	v_add_u32_e32 v2, 10, v0
	v_cndmask_b32_e64 v2, v1, v2, s[42:43]
	v_mul_i32_i24_e32 v152, 0xd00, v2
	v_lshl_add_u64 v[2:3], v[152:153], 1, v[16:17]
	v_mov_b32_e32 v56, v116
	v_mov_b32_e32 v57, v117
	v_mov_b32_e32 v58, v118
	v_mov_b32_e32 v59, v119
	v_add_u32_e32 v2, 11, v0
	v_cndmask_b32_e64 v2, v1, v2, s[42:43]
	v_mul_i32_i24_e32 v152, 0xd00, v2
	v_lshl_add_u64 v[2:3], v[152:153], 1, v[16:17]
	v_pk_add_f32 v[8:9], v[8:9], v[34:35]
	v_pk_add_f32 v[6:7], v[6:7], v[30:31]
	v_pk_add_f32 v[4:5], v[4:5], v[26:27]
	s_waitcnt vmcnt(2)
	v_cndmask_b32_e64 v40, 0, v47, s[42:43]
	v_cndmask_b32_e64 v42, 0, v46, s[42:43]
	v_cndmask_b32_e64 v46, 0, v45, s[42:43]
	v_cndmask_b32_e64 v53, 0, v44, s[42:43]
	v_lshlrev_b32_e32 v14, 16, v42
	s_waitcnt vmcnt(1)
	v_cndmask_b32_e64 v41, 0, v51, s[42:43]
	v_cndmask_b32_e64 v62, 0, v48, s[42:43]
	v_cndmask_b32_e64 v44, 0, v50, s[42:43]
	v_cndmask_b32_e64 v50, 0, v49, s[42:43]
	v_and_b32_e32 v15, 0xffff0000, v42
	s_waitcnt vmcnt(0)
	v_cndmask_b32_e64 v43, 0, v59, s[42:43]
	v_cndmask_b32_e64 v47, 0, v58, s[42:43]
	v_cndmask_b32_e64 v54, 0, v57, s[42:43]
	v_cndmask_b32_e64 v63, 0, v56, s[42:43]
	v_mov_b32_e32 v56, v120
	v_mov_b32_e32 v57, v121
	v_mov_b32_e32 v58, v122
	v_mov_b32_e32 v59, v123
	v_add_u32_e32 v2, 12, v0
	v_cndmask_b32_e64 v2, v1, v2, s[42:43]
	v_mul_i32_i24_e32 v152, 0xd00, v2
	v_lshl_add_u64 v[2:3], v[152:153], 1, v[16:17]
	v_lshlrev_b32_e32 v12, 16, v40
	v_and_b32_e32 v13, 0xffff0000, v40
	v_pk_add_f32 v[6:7], v[6:7], v[14:15]
	v_lshlrev_b32_e32 v14, 16, v44
	v_and_b32_e32 v15, 0xffff0000, v44
	v_pk_add_f32 v[4:5], v[4:5], v[12:13]
	v_lshlrev_b32_e32 v12, 16, v41
	v_and_b32_e32 v13, 0xffff0000, v41
	v_pk_add_f32 v[6:7], v[6:7], v[14:15]
	v_lshlrev_b32_e32 v14, 16, v47
	v_and_b32_e32 v15, 0xffff0000, v47
	v_pk_add_f32 v[4:5], v[4:5], v[12:13]
	v_lshlrev_b32_e32 v12, 16, v43
	v_and_b32_e32 v13, 0xffff0000, v43
	v_pk_add_f32 v[6:7], v[6:7], v[14:15]
	v_pk_add_f32 v[4:5], v[4:5], v[12:13]
	s_waitcnt vmcnt(0)
	v_cndmask_b32_e64 v45, 0, v59, s[42:43]
	v_cndmask_b32_e64 v51, 0, v58, s[42:43]
	v_cndmask_b32_e64 v64, 0, v57, s[42:43]
	v_cndmask_b32_e64 v65, 0, v56, s[42:43]
	v_mov_b32_e32 v56, v124
	v_mov_b32_e32 v57, v125
	v_mov_b32_e32 v58, v126
	v_mov_b32_e32 v59, v127
	v_add_u32_e32 v2, 13, v0
	v_cndmask_b32_e64 v2, v1, v2, s[42:43]
	v_mul_i32_i24_e32 v152, 0xd00, v2
	v_lshl_add_u64 v[2:3], v[152:153], 1, v[16:17]
	v_lshlrev_b32_e32 v14, 16, v51
	v_and_b32_e32 v15, 0xffff0000, v51
	v_lshlrev_b32_e32 v12, 16, v45
	v_and_b32_e32 v13, 0xffff0000, v45
	v_pk_add_f32 v[6:7], v[6:7], v[14:15]
	v_pk_add_f32 v[4:5], v[4:5], v[12:13]
	s_waitcnt vmcnt(0)
	v_cndmask_b32_e64 v48, 0, v59, s[42:43]
	v_cndmask_b32_e64 v55, 0, v58, s[42:43]
	v_mov_b32_e32 v58, v128
	v_mov_b32_e32 v59, v129
	v_mov_b32_e32 v60, v130
	v_mov_b32_e32 v61, v131
	v_add_u32_e32 v2, 14, v0
	v_cndmask_b32_e64 v2, v1, v2, s[42:43]
	v_add_u32_e32 v0, 15, v0
	v_mul_i32_i24_e32 v152, 0xd00, v2
	v_cndmask_b32_e64 v0, v1, v0, s[42:43]
	v_lshl_add_u64 v[2:3], v[152:153], 1, v[16:17]
	v_mul_i32_i24_e32 v152, 0xd00, v0
	v_lshl_add_u64 v[0:1], v[152:153], 1, v[16:17]
	v_cndmask_b32_e64 v66, 0, v56, s[42:43]
	v_cndmask_b32_e64 v57, 0, v57, s[42:43]
	v_lshlrev_b32_e32 v14, 16, v55
	v_and_b32_e32 v15, 0xffff0000, v55
	v_lshlrev_b32_e32 v12, 16, v48
	v_and_b32_e32 v13, 0xffff0000, v48
	v_pk_add_f32 v[6:7], v[6:7], v[14:15]
	v_pk_add_f32 v[4:5], v[4:5], v[12:13]
	s_waitcnt vmcnt(0)
	v_cndmask_b32_e64 v49, 0, v61, s[42:43]
	v_cndmask_b32_e64 v56, 0, v60, s[42:43]
	v_cndmask_b32_e64 v67, 0, v59, s[42:43]
	v_cndmask_b32_e64 v68, 0, v58, s[42:43]
	v_mov_b32_e32 v58, v132
	v_mov_b32_e32 v59, v133
	v_mov_b32_e32 v60, v134
	v_mov_b32_e32 v61, v135
	v_lshlrev_b32_e32 v14, 16, v56
	v_mov_b32_e32 v0, v136
	v_mov_b32_e32 v1, v137
	v_mov_b32_e32 v2, v138
	v_mov_b32_e32 v3, v139
	v_and_b32_e32 v15, 0xffff0000, v56
	v_lshlrev_b32_e32 v12, 16, v49
	v_and_b32_e32 v13, 0xffff0000, v49
	v_pk_add_f32 v[6:7], v[6:7], v[14:15]
	v_pk_add_f32 v[4:5], v[4:5], v[12:13]
	s_waitcnt vmcnt(1)
	v_cndmask_b32_e64 v52, 0, v61, s[42:43]
	v_cndmask_b32_e64 v60, 0, v60, s[42:43]
	s_waitcnt vmcnt(0)
	v_cndmask_b32_e64 v70, 0, v1, s[42:43]
	v_cndmask_b32_e64 v71, 0, v0, s[42:43]
	v_pk_add_f32 v[0:1], v[10:11], v[20:21]
	v_cndmask_b32_e64 v61, 0, v3, s[42:43]
	v_pk_add_f32 v[0:1], v[0:1], v[32:33]
	v_cndmask_b32_e64 v69, 0, v2, s[42:43]
	v_pk_add_f32 v[0:1], v[0:1], v[36:37]
	v_lshlrev_b32_e32 v2, 16, v53
	v_and_b32_e32 v3, 0xffff0000, v53
	v_lshlrev_b32_e32 v10, 16, v46
	v_and_b32_e32 v11, 0xffff0000, v46
	v_pk_add_f32 v[0:1], v[0:1], v[2:3]
	v_lshlrev_b32_e32 v2, 16, v62
	v_and_b32_e32 v3, 0xffff0000, v62
	v_pk_add_f32 v[8:9], v[8:9], v[10:11]
	v_lshlrev_b32_e32 v10, 16, v50
	v_and_b32_e32 v11, 0xffff0000, v50
	v_pk_add_f32 v[0:1], v[0:1], v[2:3]
	v_lshlrev_b32_e32 v2, 16, v63
	v_and_b32_e32 v3, 0xffff0000, v63
	v_pk_add_f32 v[8:9], v[8:9], v[10:11]
	v_lshlrev_b32_e32 v10, 16, v54
	v_and_b32_e32 v11, 0xffff0000, v54
	v_pk_add_f32 v[0:1], v[0:1], v[2:3]
	v_lshlrev_b32_e32 v2, 16, v65
	v_and_b32_e32 v3, 0xffff0000, v65
	v_pk_add_f32 v[8:9], v[8:9], v[10:11]
	v_lshlrev_b32_e32 v10, 16, v64
	v_and_b32_e32 v11, 0xffff0000, v64
	v_pk_add_f32 v[0:1], v[0:1], v[2:3]
	v_lshlrev_b32_e32 v2, 16, v66
	v_and_b32_e32 v3, 0xffff0000, v66
	v_pk_add_f32 v[8:9], v[8:9], v[10:11]
	v_lshlrev_b32_e32 v10, 16, v57
	v_and_b32_e32 v11, 0xffff0000, v57
	v_cndmask_b32_e64 v59, 0, v59, s[42:43]
	v_cndmask_b32_e64 v58, 0, v58, s[42:43]
	v_pk_add_f32 v[0:1], v[0:1], v[2:3]
	v_lshlrev_b32_e32 v2, 16, v68
	v_and_b32_e32 v3, 0xffff0000, v68
	v_pk_add_f32 v[8:9], v[8:9], v[10:11]
	v_lshlrev_b32_e32 v10, 16, v67
	v_and_b32_e32 v11, 0xffff0000, v67
	v_pk_add_f32 v[0:1], v[0:1], v[2:3]
	v_lshlrev_b32_e32 v2, 16, v58
	v_and_b32_e32 v3, 0xffff0000, v58
	v_pk_add_f32 v[8:9], v[8:9], v[10:11]
	v_lshlrev_b32_e32 v10, 16, v59
	v_and_b32_e32 v11, 0xffff0000, v59
	v_lshlrev_b32_e32 v14, 16, v60
	v_and_b32_e32 v15, 0xffff0000, v60
	v_lshlrev_b32_e32 v12, 16, v52
	v_and_b32_e32 v13, 0xffff0000, v52
	v_pk_add_f32 v[0:1], v[0:1], v[2:3]
	v_lshlrev_b32_e32 v2, 16, v71
	v_and_b32_e32 v3, 0xffff0000, v71
	v_pk_add_f32 v[8:9], v[8:9], v[10:11]
	v_lshlrev_b32_e32 v10, 16, v70
	v_and_b32_e32 v11, 0xffff0000, v70
	v_pk_add_f32 v[6:7], v[6:7], v[14:15]
	v_lshlrev_b32_e32 v14, 16, v69
	v_and_b32_e32 v15, 0xffff0000, v69
	v_pk_add_f32 v[4:5], v[4:5], v[12:13]
	v_lshlrev_b32_e32 v12, 16, v61
	v_and_b32_e32 v13, 0xffff0000, v61
	v_pk_add_f32 v[18:19], v[0:1], v[2:3]
	v_pk_add_f32 v[22:23], v[8:9], v[10:11]
	v_pk_add_f32 v[20:21], v[6:7], v[14:15]
	v_pk_add_f32 v[24:25], v[4:5], v[12:13]
	.p2align	6

.LBB0_942:
	s_cmp_ge_i32 s31, s68
	s_cselect_b64 s[0:1], -1, 0
	s_cmp_lt_i32 s31, s69
	s_cselect_b64 s[8:9], -1, 0
	s_and_b64 s[0:1], s[0:1], s[8:9]
	v_readlane_b32 s20, v251, 31
	v_readlane_b32 s10, v253, 11
	s_and_b64 vcc, exec, s[0:1]
	v_readlane_b32 s21, v251, 32
	v_readlane_b32 s11, v253, 12
	s_cbranch_vccz .LBB0_946
	s_lshl_b32 s0, s2, 12
	s_and_b32 s2, s0, 0x7000
	v_readlane_b32 s0, v253, 10
	s_add_i32 s0, s2, s0
	v_readlane_b32 s1, v251, 24
	s_add_i32 s3, s0, s1
	s_and_b64 s[0:1], s[10:11], exec
	v_readlane_b32 s0, v251, 25
	v_readlane_b32 s1, v251, 26
	s_cselect_b32 s0, s3, s0
	s_add_i32 s1, s2, 0x1000
	s_and_b64 s[2:3], s[10:11], exec
	s_cselect_b32 s3, s1, 0x8000
	s_cmp_ge_i32 s0, s3
	s_cbranch_scc1 .LBB0_946
	v_readlane_b32 s12, v251, 0
	v_readlane_b32 s13, v251, 1
	v_readlane_b32 s14, v251, 2
	v_readlane_b32 s15, v251, 3
	v_readlane_b32 s16, v251, 4
	v_readlane_b32 s17, v251, 5
	v_lshlrev_b32_e32 v20, 5, v223
	v_readlane_b32 s18, v251, 6
	v_readlane_b32 s19, v251, 7
	s_mov_b64 s[12:13], s[16:17]
	s_waitcnt lgkmcnt(0)
	global_load_dwordx4 v[0:3], v20, s[12:13] offset:16
	global_load_dwordx4 v[4:7], v20, s[12:13]
	global_load_dwordx4 v[8:11], v20, s[12:13] offset:2064
	global_load_dwordx4 v[12:15], v20, s[12:13] offset:2048
	v_cmp_lt_i32_e32 vcc, v206, v205
	v_mov_b32_e32 v21, 0
	v_and_b32_e32 v16, 3, v222
	v_cndmask_b32_e32 v17, v204, v206, vcc
	v_lshlrev_b32_e32 v23, 2, v17
	v_xor_b32_e32 v17, 2, v204
	v_cmp_lt_i32_e32 vcc, v17, v205
	s_and_b64 s[10:11], s[10:11], exec
	v_lshlrev_b32_e32 v16, 4, v16
	v_cndmask_b32_e32 v17, v204, v17, vcc
	v_lshlrev_b32_e32 v24, 2, v17
	v_mov_b32_e32 v17, v21
	v_lshl_add_u64 v[16:17], s[20:21], 0, v[16:17]
	s_mov_b64 s[10:11], 0x200000
	v_mov_b32_e32 v155, v21
	s_mov_b64 s[14:15], s[18:19]
	v_readlane_b32 s1, v251, 57
	v_lshl_add_u64 v[16:17], v[16:17], 0, s[10:11]
	v_lshl_add_u64 v[18:19], s[20:21], 0, v[154:155]
	s_mov_b64 s[10:11], 0x6400000
	s_cselect_b32 s12, 0x100, s1
	v_lshl_add_u64 v[18:19], v[18:19], 0, s[10:11]
	v_lshl_add_u64 v[20:21], s[14:15], 0, v[20:21]
	s_mov_b32 s2, 0x3a800000
	v_mov_b32_e32 v22, 0x358637bd
	s_mov_b32 s13, 0x800000
	s_mov_b32 s1, s0
	v_mov_b32_e32 v124, s1
	v_ashrrev_i32_e32 v125, 31, v124
	v_lshlrev_b64 v[126:127], 6, v[124:125]
	v_lshl_add_u64 v[126:127], v[16:17], 0, v[126:127]
	global_load_dwordx4 v[100:103], v[126:127], off
	v_lshlrev_b64 v[128:129], 11, v[124:125]
	v_lshl_add_u64 v[128:129], v[18:19], 0, v[128:129]
	global_load_dwordx4 v[104:107], v[128:129], off
	global_load_dwordx4 v[108:111], v[128:129], off offset:1024
	s_add_i32 s1, s1, s12
	v_mov_b32_e32 v124, s1
	v_ashrrev_i32_e32 v125, 31, v124
	v_lshlrev_b64 v[126:127], 6, v[124:125]
	v_lshl_add_u64 v[126:127], v[16:17], 0, v[126:127]
	global_load_dwordx4 v[112:115], v[126:127], off
	v_lshlrev_b64 v[128:129], 11, v[124:125]
	v_lshl_add_u64 v[128:129], v[18:19], 0, v[128:129]
	global_load_dwordx4 v[116:119], v[128:129], off
	global_load_dwordx4 v[120:123], v[128:129], off offset:1024
	s_waitcnt vmcnt(0)
	.p2align	6
